# tile rebalancing (in_gemm half-width tiles, mix_a sub-loop rotation) and epilogue de-serialisation (sgu u*Z stores, Vt pointer reloads, mix_b store pointers)
# speedup vs baseline: 1.2793x; 1.0080x over previous
; #define XCD_FOR(u, T)                                                                                         \
;   for (int _x = bid_() & 7, _gb = gridDim.x >> 3, _hi = (int)(((long)(_x + 1) * (T)) >> 3),                    \
;            u = (int)(((long)_x * (T)) >> 3) + (bid_() >> 3);                                                  \
;        u < _hi; u += _gb)
; __device__ __forceinline__ void phase_in_gemm(const Params& p, int l, unsigned char* smem) {
;     ...
;   XCD_FOR(t, 132) {
;     const int row_base = t * 128;
;     auto epi = [&](f32x4(&acc)[4][2], int r0, int c0) {
;       auto vf = [&](int, int, float v) { return v; };
;       auto rp = [&](int r) -> u16* { return p.PX + (size_t)(row_base + r) * 1024 + 896; };
;       epi_staged_bf16<2>(acc, r0, c0, smem, vf, rp);
;     };
;     gemm_tile<2, false>(p.H + (size_t)row_base * 1024, 1024, nullptr, 128, W + (size_t)11 * 128 * 1024, 1024, 1024, smem, epi);
;   }
.LBB0_485:
	s_mov_b32 s0, s2
	s_and_b32 s0, s0, 7
	s_mov_b32 s8, s2
	s_mul_i32 s1, s0, 0x84
	s_add_i32 s0, s1, 0x84
	s_lshr_b32 s1, s1, 3
	s_ashr_i32 s8, s8, 3
	s_sub_i32 s8, 63, s8
	s_cmp_gt_i32 s8, 9
	s_cbranch_scc1 .LBB0_490
	s_lshr_b32 s0, s0, 3
	s_add_i32 s1, s1, s8
	s_cmp_ge_i32 s1, s0
	s_cbranch_scc1 .LBB0_490
	s_mov_b64 s[8:9], 0x2c0000
	v_mov_b32_e32 v0, 0x300000
	v_lshl_add_u64 v[82:83], v[132:133], 0, s[8:9]
	v_mad_u64_u32 v[84:85], s[8:9], s36, v0, v[130:131]
	s_lshl_b32 s38, s1, 7

; template <int NT, bool BKN, bool MASK = false, bool ROWSS = false, class Epi> ...
;     ...
;   float ss_[4] = {0.f, 0.f, 0.f, 0.f};
;   int stk_ = 0;
;   f32x4 acc[4][NT];
; #pragma unroll
;   for (int i = 0; i < 4; ++i)
; #pragma unroll
;     for (int j = 0; j < NT; ++j) acc[i][j] = (f32x4){0.f, 0.f, 0.f, 0.f};
;   const int nk = K >> 6;
;   const int nkm1 = nk - 1;
;   __syncthreads();
;   GEMM_LOAD(ra0, rb0, 0);
;   GEMM_LOAD(ra1, rb1, 1);
;   GEMM_STORE(ra0, rb0, 0);
;   GEMM_LOAD(ra0, rb0, (2 < nkm1 ? 2 : nkm1));
;   __syncthreads();
;   for (int kt = 0; kt < nk - 2; kt += 2) {
;     GEMM_COMPUTE(0);
;     GEMM_STORE(ra1, rb1, 1);
;     GEMM_LOAD(ra1, rb1, kt + 3);
;     __syncthreads();
;     GEMM_COMPUTE(1);
;     GEMM_STORE(ra0, rb0, 0);
;     GEMM_LOAD(ra0, rb0, (kt + 4 < nkm1 ? kt + 4 : nkm1));
;     __syncthreads();
;   }
.LBB0_488:
	s_nop 0
	ds_read_b128 v[112:115], v109
	ds_read_b128 v[116:119], v109 offset:2048
	ds_read_b128 v[120:123], v109 offset:4096
	ds_read_b128 v[124:127], v109 offset:6144
	ds_read_b128 v[128:131], v108 offset:16384
	ds_read_b128 v[132:135], v108 offset:18432
	s_mov_b32 s9, 0x2c0000
	s_add_i32 s8, s8, 2
	s_waitcnt lgkmcnt(0)
	v_mfma_f32_16x16x32_bf16 v[78:81], v[112:115], v[128:131], v[78:81]
	s_waitcnt lgkmcnt(0)
	v_mfma_f32_16x16x32_bf16 v[74:77], v[112:115], v[132:135], v[74:77]
	v_mfma_f32_16x16x32_bf16 v[70:73], v[116:119], v[128:131], v[70:73]
	v_mfma_f32_16x16x32_bf16 v[66:69], v[116:119], v[132:135], v[66:69]
	v_mfma_f32_16x16x32_bf16 v[62:65], v[120:123], v[128:131], v[62:65]
	v_mfma_f32_16x16x32_bf16 v[58:61], v[120:123], v[132:135], v[58:61]
	v_mfma_f32_16x16x32_bf16 v[112:115], v[124:127], v[128:131], v[54:57]
	v_mfma_f32_16x16x32_bf16 v[116:119], v[124:127], v[132:135], v[50:53]
	s_nop 2
	ds_read_b128 v[50:53], v107
	ds_read_b128 v[54:57], v107 offset:2048
	ds_read_b128 v[120:123], v107 offset:4096
	ds_read_b128 v[124:127], v107 offset:6144
	ds_read_b128 v[128:131], v106 offset:16384
	ds_read_b128 v[132:135], v106 offset:18432
	s_waitcnt vmcnt(0)
	ds_write_b128 v110, v[2:5] offset:32768
	ds_write_b128 v110, v[10:13] offset:36864
	ds_write_b128 v110, v[14:17] offset:40960
	ds_write_b128 v110, v[18:21] offset:45056
	ds_write_b128 v110, v[6:9] offset:49152
	ds_write_b128 v110, v[22:25] offset:53248
	v_lshl_add_u64 v[6:7], v[100:101], 0, v[0:1]
	v_add_co_u32_e32 v8, vcc, s15, v6
	global_load_dwordx4 v[2:5], v[6:7], off offset:384
	s_nop 0
	v_addc_co_u32_e32 v9, vcc, 0, v7, vcc
	global_load_dwordx4 v[10:13], v[8:9], off offset:384
	v_add_co_u32_e32 v8, vcc, s16, v6
	v_lshl_add_u64 v[22:23], v[98:99], 0, v[0:1]
	s_nop 0
	v_addc_co_u32_e32 v9, vcc, 0, v7, vcc
	v_add_co_u32_e32 v6, vcc, s17, v6
	global_load_dwordx4 v[14:17], v[8:9], off offset:384
	s_nop 0
	v_addc_co_u32_e32 v7, vcc, 0, v7, vcc
	global_load_dwordx4 v[18:21], v[6:7], off offset:384
	v_add_co_u32_e32 v6, vcc, s9, v22
	s_mov_b32 s9, 0x2d0000
	s_nop 0
	v_addc_co_u32_e32 v7, vcc, 0, v23, vcc
	v_add_co_u32_e32 v22, vcc, s9, v22
	s_waitcnt lgkmcnt(0)
	v_mfma_f32_16x16x32_bf16 v[78:81], v[50:53], v[128:131], v[78:81]
	v_addc_co_u32_e32 v23, vcc, 0, v23, vcc
	global_load_dwordx4 v[6:9], v[6:7], off offset:384
	v_mfma_f32_16x16x32_bf16 v[74:77], v[50:53], v[132:135], v[74:77]
	global_load_dwordx4 v[22:25], v[22:23], off offset:384
	s_waitcnt lgkmcnt(0)
	s_barrier
	v_mfma_f32_16x16x32_bf16 v[70:73], v[54:57], v[128:131], v[70:73]
	s_min_u32 s9, s8, 11
	s_lshl_b32 s94, s9, 7
	v_mfma_f32_16x16x32_bf16 v[66:69], v[54:57], v[132:135], v[66:69]
	v_lshl_add_u64 v[98:99], v[98:99], 0, s[6:7]
	v_lshl_add_u64 v[100:101], v[100:101], 0, s[6:7]
	s_cmp_lt_u32 s8, 12
	v_mfma_f32_16x16x32_bf16 v[50:53], v[120:123], v[128:131], v[62:65]
	v_mfma_f32_16x16x32_bf16 v[54:57], v[120:123], v[132:135], v[58:61]
	v_mfma_f32_16x16x32_bf16 v[58:61], v[124:127], v[128:131], v[112:115]
	v_mfma_f32_16x16x32_bf16 v[62:65], v[124:127], v[132:135], v[116:119]
	s_nop 1
	ds_read_b128 v[112:115], v109 offset:32768
	ds_read_b128 v[116:119], v109 offset:34816
	ds_read_b128 v[120:123], v109 offset:36864
	ds_read_b128 v[124:127], v109 offset:38912
	ds_read_b128 v[128:131], v108 offset:49152
	ds_read_b128 v[132:135], v108 offset:51200
	s_waitcnt lgkmcnt(0)
	v_mfma_f32_16x16x32_bf16 v[78:81], v[112:115], v[128:131], v[78:81]
	v_mfma_f32_16x16x32_bf16 v[74:77], v[112:115], v[132:135], v[74:77]
	v_mfma_f32_16x16x32_bf16 v[70:73], v[116:119], v[128:131], v[70:73]
	v_mfma_f32_16x16x32_bf16 v[66:69], v[116:119], v[132:135], v[66:69]
	v_mfma_f32_16x16x32_bf16 v[50:53], v[120:123], v[128:131], v[50:53]
	v_mfma_f32_16x16x32_bf16 v[54:57], v[120:123], v[132:135], v[54:57]
	v_mfma_f32_16x16x32_bf16 v[112:115], v[124:127], v[128:131], v[58:61]
	v_mfma_f32_16x16x32_bf16 v[116:119], v[124:127], v[132:135], v[62:65]
	s_nop 1
	ds_read_b128 v[58:61], v107 offset:32768
	ds_read_b128 v[62:65], v107 offset:34816
	ds_read_b128 v[120:123], v107 offset:36864
	ds_read_b128 v[124:127], v107 offset:38912
	ds_read_b128 v[128:131], v106 offset:49152
	ds_read_b128 v[132:135], v106 offset:51200
	ds_write_b128 v110, v[26:29]
	ds_write_b128 v110, v[34:37] offset:4096
	ds_write_b128 v110, v[38:41] offset:8192
	ds_write_b128 v110, v[42:45] offset:12288
	ds_write_b128 v110, v[30:33] offset:16384
	ds_write_b128 v110, v[46:49] offset:20480
	v_lshl_add_u64 v[26:27], v[90:91], 0, s[94:95]
	v_lshl_add_u64 v[30:31], v[92:93], 0, s[94:95]
	global_load_dwordx4 v[26:29], v[26:27], off offset:512
	v_lshl_add_u64 v[46:47], v[88:89], 0, s[94:95]
	global_load_dwordx4 v[34:37], v[30:31], off offset:512
	v_lshl_add_u64 v[30:31], v[94:95], 0, s[94:95]
	global_load_dwordx4 v[38:41], v[30:31], off offset:512
	v_lshl_add_u64 v[30:31], v[96:97], 0, s[94:95]
	global_load_dwordx4 v[42:45], v[30:31], off offset:512
	v_lshl_add_u64 v[30:31], v[86:87], 0, s[94:95]
	global_load_dwordx4 v[30:33], v[30:31], off offset:512
	s_waitcnt lgkmcnt(0)
	v_mfma_f32_16x16x32_bf16 v[78:81], v[58:61], v[128:131], v[78:81]
	global_load_dwordx4 v[46:49], v[46:47], off offset:512
	s_waitcnt lgkmcnt(0)
	s_barrier
	v_mfma_f32_16x16x32_bf16 v[74:77], v[58:61], v[132:135], v[74:77]
	v_mfma_f32_16x16x32_bf16 v[70:73], v[62:65], v[128:131], v[70:73]
	v_mfma_f32_16x16x32_bf16 v[66:69], v[62:65], v[132:135], v[66:69]
	v_mfma_f32_16x16x32_bf16 v[62:65], v[120:123], v[128:131], v[50:53]
	v_mfma_f32_16x16x32_bf16 v[58:61], v[120:123], v[132:135], v[54:57]
	v_mfma_f32_16x16x32_bf16 v[54:57], v[124:127], v[128:131], v[112:115]
	v_mfma_f32_16x16x32_bf16 v[50:53], v[124:127], v[132:135], v[116:119]
	s_cbranch_scc1 .LBB0_488
; #define XCD_FOR(u, T)                                                                                         \
;   for (int _x = bid_() & 7, _gb = gridDim.x >> 3, _hi = (int)(((long)(_x + 1) * (T)) >> 3),                    \
;            u = (int)(((long)_x * (T)) >> 3) + (bid_() >> 3);                                                  \
;        u < _hi; u += _gb)
; template <int NT, bool BKN, bool MASK = false, bool ROWSS = false, class Epi> ...
;     ...
;   GEMM_COMPUTE(0);
;   GEMM_STORE(ra1, rb1, 1);
;   __syncthreads();
;   GEMM_COMPUTE(1);
; __device__ __forceinline__ void phase_in_gemm(const Params& p, int l, unsigned char* smem) {
;     ...
;   XCD_FOR(t, 132) {
;     const int row_base = t * 128;
	s_waitcnt vmcnt(0)
	ds_read_b128 v[26:29], v109
	ds_read_b128 v[30:33], v109 offset:2048
	ds_read_b128 v[34:37], v109 offset:4096
	ds_read_b128 v[38:41], v109 offset:6144
	ds_read_b128 v[42:45], v108 offset:16384
	ds_read_b128 v[46:49], v108 offset:18432
	v_lshlrev_b32_e32 v0, 6, v105
	s_add_i32 s1, s1, 10
	s_waitcnt lgkmcnt(1)
	v_mfma_f32_16x16x32_bf16 v[78:81], v[26:29], v[42:45], v[78:81]
	s_waitcnt lgkmcnt(0)
	v_mfma_f32_16x16x32_bf16 v[26:29], v[26:29], v[46:49], v[74:77]
	v_mfma_f32_16x16x32_bf16 v[70:73], v[30:33], v[42:45], v[70:73]
	v_mfma_f32_16x16x32_bf16 v[30:33], v[30:33], v[46:49], v[66:69]
	v_mfma_f32_16x16x32_bf16 v[62:65], v[34:37], v[42:45], v[62:65]
	v_mfma_f32_16x16x32_bf16 v[34:37], v[34:37], v[46:49], v[58:61]
	v_mfma_f32_16x16x32_bf16 v[42:45], v[38:41], v[42:45], v[54:57]
	v_mfma_f32_16x16x32_bf16 v[38:41], v[38:41], v[46:49], v[50:53]
	ds_read_b128 v[46:49], v107
	s_nop 1
	ds_read_b128 v[50:53], v107 offset:2048
	ds_read_b128 v[54:57], v107 offset:4096
	ds_read_b128 v[58:61], v107 offset:6144
	ds_read_b128 v[66:69], v106 offset:16384
	ds_read_b128 v[74:77], v106 offset:18432
	ds_write_b128 v110, v[2:5] offset:32768
	ds_write_b128 v110, v[10:13] offset:36864
	ds_write_b128 v110, v[14:17] offset:40960
	ds_write_b128 v110, v[18:21] offset:45056
	ds_write_b128 v110, v[6:9] offset:49152
	ds_write_b128 v110, v[22:25] offset:53248
	s_waitcnt lgkmcnt(0)
	s_barrier
	ds_read_b128 v[2:5], v109 offset:32768
	ds_read_b128 v[6:9], v109 offset:34816
	ds_read_b128 v[10:13], v109 offset:36864
	ds_read_b128 v[14:17], v109 offset:38912
	ds_read_b128 v[18:21], v108 offset:49152
	ds_read_b128 v[22:25], v108 offset:51200
	v_mfma_f32_16x16x32_bf16 v[78:81], v[46:49], v[66:69], v[78:81]
	v_mfma_f32_16x16x32_bf16 v[26:29], v[46:49], v[74:77], v[26:29]
	v_mfma_f32_16x16x32_bf16 v[46:49], v[50:53], v[66:69], v[70:73]
	v_mfma_f32_16x16x32_bf16 v[30:33], v[50:53], v[74:77], v[30:33]
	v_mfma_f32_16x16x32_bf16 v[50:53], v[54:57], v[66:69], v[62:65]
	v_mfma_f32_16x16x32_bf16 v[34:37], v[54:57], v[74:77], v[34:37]
	v_mfma_f32_16x16x32_bf16 v[42:45], v[58:61], v[66:69], v[42:45]
	v_mfma_f32_16x16x32_bf16 v[38:41], v[58:61], v[74:77], v[38:41]
	s_waitcnt lgkmcnt(1)
	v_mfma_f32_16x16x32_bf16 v[54:57], v[2:5], v[18:21], v[78:81]
	s_waitcnt lgkmcnt(0)
	v_mfma_f32_16x16x32_bf16 v[2:5], v[2:5], v[22:25], v[26:29]
	v_mfma_f32_16x16x32_bf16 v[26:29], v[6:9], v[18:21], v[46:49]
	v_mfma_f32_16x16x32_bf16 v[6:9], v[6:9], v[22:25], v[30:33]
	v_mfma_f32_16x16x32_bf16 v[30:33], v[10:13], v[18:21], v[50:53]
	v_mfma_f32_16x16x32_bf16 v[10:13], v[10:13], v[22:25], v[34:37]
	v_mfma_f32_16x16x32_bf16 v[18:21], v[14:17], v[18:21], v[42:45]
	v_mfma_f32_16x16x32_bf16 v[14:17], v[14:17], v[22:25], v[38:41]
	ds_read_b128 v[22:25], v107 offset:32768
	ds_read_b128 v[34:37], v107 offset:34816
	s_nop 0
	ds_read_b128 v[38:41], v107 offset:36864
	ds_read_b128 v[42:45], v107 offset:38912
	ds_read_b128 v[46:49], v106 offset:49152
	ds_read_b128 v[50:53], v106 offset:51200
	s_waitcnt lgkmcnt(1)
	v_mfma_f32_16x16x32_bf16 v[54:57], v[22:25], v[46:49], v[54:57]
	s_waitcnt lgkmcnt(0)
	v_mfma_f32_16x16x32_bf16 v[2:5], v[22:25], v[50:53], v[2:5]
	v_mfma_f32_16x16x32_bf16 v[22:25], v[34:37], v[46:49], v[26:29]
	v_mfma_f32_16x16x32_bf16 v[26:29], v[38:41], v[46:49], v[30:33]
	s_nop 2
	v_lshl_or_b32 v30, v104, 2, v0
	v_lshlrev_b32_e32 v0, 1, v103
	v_lshl_or_b32 v0, v102, 6, v0
	v_mov_b32_e32 v32, v187
	v_mad_u64_u32 v[30:31], s[8:9], v30, s96, v[0:1]
	v_cvt_pk_bf16_f32 v0, v55, s0
	s_barrier
; __device__ __forceinline__ u16 f2bf(float f) { return (u16)(pack2(f, 0.f) & 0xffffu); }
; __device__ __forceinline__ int tid_() { int t = threadIdx.x; asm volatile("" : "+v"(t)); return t; }
; template <int NT, class VF, class RP>
; __device__ __forceinline__ void epi_staged_bf16(f32x4 (&acc)[4][NT], int r0, int c0, unsigned char* smem, VF vf, RP rowptr) {
;   constexpr int BN = NT * 32, PITCH = BN + 8, CPR = BN / 8;
;   u16* Ts = (u16*)smem;
;   const int t = tid_();
;   __syncthreads();
; #pragma unroll
;   for (int mi = 0; mi < 4; ++mi)
; #pragma unroll
;     for (int ni = 0; ni < NT; ++ni)
; #pragma unroll
;       for (int j = 0; j < 4; ++j) {
;         const int r = r0 + mi * 16 + j, c = c0 + ni * 16;
;         Ts[r * PITCH + c] = f2bf(vf(r, c, acc[mi][ni][j]));
;       }
;   __syncthreads();
; #pragma unroll
;   for (int i = 0; i < CPR / 2; ++i) {
;     const int c = t + 256 * i, row = c / CPR, ch = c % CPR;
;     u16* d = rowptr(row);
;     if (d) *(u32x4*)(d + ch * 8) = *(const u32x4*)(Ts + row * PITCH + ch * 8);
;   }
; __device__ __forceinline__ void phase_in_gemm(const Params& p, int l, unsigned char* smem) {
;     ...
;       auto rp = [&](int r) -> u16* { return p.PX + (size_t)(row_base + r) * 1024 + 896; };
;       epi_staged_bf16<2>(acc, r0, c0, smem, vf, rp);
	ds_write_b16 v30, v0 offset:144
	v_cvt_pk_bf16_f32 v0, v56, s0
	ds_write_b16 v30, v0 offset:288
	v_cvt_pk_bf16_f32 v0, v57, s0
	ds_write_b16 v30, v0 offset:432
	v_cvt_pk_bf16_f32 v0, v2, s0
	ds_write_b16 v30, v0 offset:32
	v_cvt_pk_bf16_f32 v0, v3, s0
	ds_write_b16 v30, v0 offset:176
	v_cvt_pk_bf16_f32 v0, v4, s0
	ds_write_b16 v30, v0 offset:320
	v_cvt_pk_bf16_f32 v0, v5, s0
	v_mfma_f32_16x16x32_bf16 v[6:9], v[34:37], v[50:53], v[6:9]
	ds_write_b16 v30, v0 offset:464
	v_cvt_pk_bf16_f32 v0, v22, s0
	ds_write_b16 v30, v0 offset:2304
	v_cvt_pk_bf16_f32 v0, v23, s0
	ds_write_b16 v30, v0 offset:2448
	v_cvt_pk_bf16_f32 v0, v24, s0
	ds_write_b16 v30, v0 offset:2592
	v_cvt_pk_bf16_f32 v0, v25, s0
	ds_write_b16 v30, v0 offset:2736
	v_cvt_pk_bf16_f32 v0, v6, s0
	ds_write_b16 v30, v0 offset:2336
	v_cvt_pk_bf16_f32 v0, v7, s0
	ds_write_b16 v30, v0 offset:2480
	v_cvt_pk_bf16_f32 v0, v8, s0
	ds_write_b16 v30, v0 offset:2624
	v_cvt_pk_bf16_f32 v0, v9, s0
	v_mfma_f32_16x16x32_bf16 v[10:13], v[38:41], v[50:53], v[10:13]
	ds_write_b16 v30, v0 offset:2768
	v_cvt_pk_bf16_f32 v0, v26, s0
	ds_write_b16 v30, v0 offset:4608
	v_cvt_pk_bf16_f32 v0, v27, s0
	ds_write_b16 v30, v0 offset:4752
	v_cvt_pk_bf16_f32 v0, v28, s0
	ds_write_b16 v30, v0 offset:4896
	v_cvt_pk_bf16_f32 v0, v29, s0
	v_mfma_f32_16x16x32_bf16 v[18:21], v[42:45], v[46:49], v[18:21]
	ds_write_b16 v30, v0 offset:5040
	v_cvt_pk_bf16_f32 v0, v10, s0
	ds_write_b16 v30, v0 offset:4640
	v_cvt_pk_bf16_f32 v0, v11, s0
	ds_write_b16 v30, v0 offset:4784
	v_cvt_pk_bf16_f32 v0, v12, s0
	ds_write_b16 v30, v0 offset:4928
	v_cvt_pk_bf16_f32 v0, v13, s0
	v_mfma_f32_16x16x32_bf16 v[14:17], v[42:45], v[50:53], v[14:17]
	ds_write_b16 v30, v0 offset:5072
	v_cvt_pk_bf16_f32 v0, v18, s0
	ds_write_b16 v30, v0 offset:6912
	v_cvt_pk_bf16_f32 v0, v19, s0
	ds_write_b16 v30, v0 offset:7056
	v_cvt_pk_bf16_f32 v0, v20, s0
	ds_write_b16 v30, v0 offset:7200
	v_cvt_pk_bf16_f32 v0, v21, s0
	ds_write_b16 v30, v0 offset:7344
	v_cvt_pk_bf16_f32 v0, v14, s0
	ds_write_b16 v30, v0 offset:6944
	v_cvt_pk_bf16_f32 v0, v15, s0
	ds_write_b16 v30, v0 offset:7088
	v_cvt_pk_bf16_f32 v0, v16, s0
	v_cvt_pk_bf16_f32 v33, v54, s0
	ds_write_b16 v30, v0 offset:7232
	v_cvt_pk_bf16_f32 v0, v17, s0
	v_mov_b64_e32 v[2:3], s[4:5]
	ds_write_b16 v30, v33
	ds_write_b16 v30, v0 offset:7376
	s_waitcnt lgkmcnt(0)
	s_barrier
	s_load_dwordx2 s[100:101], s[4:5], 0x120
	s_waitcnt lgkmcnt(0)
	v_mov_b32_e32 v4, s100
	v_mov_b32_e32 v5, s101
	v_ashrrev_i32_e32 v0, 31, v32
	v_lshrrev_b32_e32 v0, 29, v0
	v_add_u32_e32 v0, v32, v0
	v_ashrrev_i32_e32 v10, 3, v0
	v_add_u32_e32 v6, s40, v10
	v_ashrrev_i32_e32 v7, 31, v6
	v_lshlrev_b64 v[6:7], 11, v[6:7]
	v_and_b32_e32 v0, -8, v0
	v_sub_u32_e32 v0, v32, v0
	s_nop 0
	s_add_i32 s38, s38, 0x500
	s_cmp_lt_i32 s1, s0
	s_waitcnt lgkmcnt(0)
	v_lshl_add_u64 v[8:9], v[4:5], 0, v[6:7]
	v_mul_lo_u32 v4, v10, s96
	v_lshlrev_b32_e32 v10, 3, v0
	v_lshl_add_u32 v0, v0, 4, v4
	ds_read_b128 v[4:7], v0
	v_ashrrev_i32_e32 v11, 31, v10
	v_lshl_add_u64 v[8:9], v[10:11], 1, v[8:9]
	v_add_u32_e32 v0, 0x100, v32
	s_waitcnt lgkmcnt(0)
	global_store_dwordx4 v[8:9], v[4:7], off offset:1792
	s_nop 1
	v_ashrrev_i32_e32 v4, 31, v0
	v_lshrrev_b32_e32 v4, 29, v4
	v_add_u32_e32 v10, v0, v4
	s_load_dwordx2 s[100:101], s[4:5], 0x120
	s_waitcnt lgkmcnt(0)
	v_mov_b32_e32 v4, s100
	v_mov_b32_e32 v5, s101
	v_ashrrev_i32_e32 v11, 3, v10
	v_add_u32_e32 v6, s40, v11
	v_ashrrev_i32_e32 v7, 31, v6
	v_lshlrev_b64 v[6:7], 11, v[6:7]
	s_waitcnt lgkmcnt(0)
	v_lshl_add_u64 v[8:9], v[4:5], 0, v[6:7]
	v_and_b32_e32 v4, -8, v10
	v_sub_u32_e32 v0, v0, v4
	v_mul_lo_u32 v4, v11, s96
	v_lshlrev_b32_e32 v10, 3, v0
	v_lshl_add_u32 v0, v0, 4, v4
	ds_read_b128 v[4:7], v0
	v_ashrrev_i32_e32 v11, 31, v10
	v_lshl_add_u64 v[8:9], v[10:11], 1, v[8:9]
	v_add_u32_e32 v0, 0x200, v32
	s_waitcnt lgkmcnt(0)
	global_store_dwordx4 v[8:9], v[4:7], off offset:1792
	s_nop 1
	v_ashrrev_i32_e32 v4, 31, v0
	v_lshrrev_b32_e32 v4, 29, v4
	v_add_u32_e32 v10, v0, v4
	s_load_dwordx2 s[100:101], s[4:5], 0x120
	s_waitcnt lgkmcnt(0)
	v_mov_b32_e32 v4, s100
	v_mov_b32_e32 v5, s101
	v_ashrrev_i32_e32 v11, 3, v10
	v_add_u32_e32 v6, s40, v11
	v_ashrrev_i32_e32 v7, 31, v6
	v_lshlrev_b64 v[6:7], 11, v[6:7]
	s_waitcnt lgkmcnt(0)
	v_lshl_add_u64 v[8:9], v[4:5], 0, v[6:7]
	v_and_b32_e32 v4, -8, v10
	v_sub_u32_e32 v0, v0, v4
	v_mul_lo_u32 v4, v11, s96
	v_lshlrev_b32_e32 v10, 3, v0
	v_lshl_add_u32 v0, v0, 4, v4
	ds_read_b128 v[4:7], v0
	v_ashrrev_i32_e32 v11, 31, v10
	v_lshl_add_u64 v[8:9], v[10:11], 1, v[8:9]
	v_add_u32_e32 v0, 0x300, v32
	s_waitcnt lgkmcnt(0)
	global_store_dwordx4 v[8:9], v[4:7], off offset:1792
	global_load_dwordx2 v[2:3], v[2:3], off offset:288
	s_nop 0
	v_ashrrev_i32_e32 v4, 31, v0
	v_lshrrev_b32_e32 v4, 29, v4
	v_add_u32_e32 v8, v0, v4
	v_ashrrev_i32_e32 v9, 3, v8
	v_add_u32_e32 v4, s40, v9
	v_ashrrev_i32_e32 v5, 31, v4
	v_lshlrev_b64 v[4:5], 11, v[4:5]
	s_waitcnt vmcnt(0) lgkmcnt(0)
	v_lshl_add_u64 v[6:7], v[2:3], 0, v[4:5]
	v_and_b32_e32 v2, -8, v8
	v_sub_u32_e32 v0, v0, v2
	v_mul_lo_u32 v2, v9, s96
	v_lshlrev_b32_e32 v8, 3, v0
	v_lshl_add_u32 v0, v0, 4, v2
	ds_read_b128 v[2:5], v0
	v_ashrrev_i32_e32 v9, 31, v8
	v_lshl_add_u64 v[6:7], v[8:9], 1, v[6:7]
	s_waitcnt lgkmcnt(0)
	global_store_dwordx4 v[6:7], v[2:5], off offset:1792
	s_cbranch_scc1 .LBB0_487

; #define XCD_FOR(u, T)                                                                                         \
;   for (int _x = bid_() & 7, _gb = gridDim.x >> 3, _hi = (int)(((long)(_x + 1) * (T)) >> 3),                    \
;            u = (int)(((long)_x * (T)) >> 3) + (bid_() >> 3);                                                  \
;        u < _hi; u += _gb)
; __device__ __forceinline__ void phase_mix_a(const Params& p, int l, bool last, unsigned char* smem) {
;     ...
;     XCD_FOR(t, 132 * 8) {
;       const int mt = t >> 3, nt = t & 7, row_base = mt * 128, h = nt >> 1;
;       const int b = row_batch(row_base), pos_base = row_pos(row_base);
.LBB0_569:
	s_waitcnt vmcnt(0) lgkmcnt(0)
	v_mov_b64_e32 v[2:3], s[40:41]
	global_load_dwordx2 v[2:3], v[2:3], off offset:208
	s_mov_b32 s0, s2
	s_and_b32 s0, s0, 7
	s_mul_i32 s1, s0, 0x420
	s_addk_i32 s1, 0x420
	s_lshr_b32 s8, s1, 3
	s_mov_b32 s1, s2
	s_mul_i32 s4, s0, 0x84
	s_ashr_i32 s1, s1, 3
	s_sub_i32 s1, s1, 35
	s_and_b32 s1, s1, 63
	s_add_i32 s9, s4, s1
	s_cmp_ge_i32 s9, s8
	s_mov_b32 s37, s95
	s_cbranch_scc1 .LBB0_600
	s_lshl_b64 s[4:5], s[36:37], 18
	s_mulk_i32 s0, 0x840
	s_lshl_b32 s1, s1, 4
	s_waitcnt vmcnt(0) lgkmcnt(0)
	v_lshl_add_u64 v[90:91], v[2:3], 0, s[4:5]
	s_add_i32 s18, s0, s1
	s_branch .LBB0_573

; template <class RP>
; __device__ __forceinline__ void epi_staged_bf16_T(f32x4 (&acc)[4][4], int r0, int c0, unsigned char* smem, RP colptr) {
;     ...
;   __syncthreads();
; #pragma unroll
;   for (int mi = 0; mi < 4; ++mi)
; #pragma unroll
;     for (int ni = 0; ni < 4; ++ni) {
;       u32x2 pk;
;       pk.x = pack2(acc[mi][ni][0], acc[mi][ni][1]);
;       pk.y = pack2(acc[mi][ni][2], acc[mi][ni][3]);
;       *(u32x2*)(Ts + (c0 + ni * 16) * PITCH + r0 + mi * 16) = pk;
;     }
;   __syncthreads();
; __device__ __forceinline__ void phase_mix_a(const Params& p, int l, bool last, unsigned char* smem) {
;     ...
; #pragma unroll
;           for (int mi = 0; mi < 4; ++mi)
; #pragma unroll
;             for (int j = 0; j < 4; ++j) {
;               const float sc = rs[r0 + mi * 16 + j];
; #pragma unroll
;               for (int ni = 0; ni < 4; ++ni) acc[mi][ni][j] *= sc;
;             }
;           auto cp = [&](int c) -> u16* { return p.Vt + ((size_t)(b * 4 + h) * 128 + c) * NPOS + pos_base; };
;           epi_staged_bf16_T(acc, r0, c0, smem, cp);
.LBB0_581:
	s_or_b64 exec, exec, s[0:1]
	s_lshr_b32 s5, s19, 1
	v_lshlrev_b32_e32 v0, 6, v0
	s_bitcmp1_b32 s9, 0
	v_lshl_or_b32 v18, v93, 2, v0
	s_cselect_b64 s[34:35], -1, 0
	s_waitcnt lgkmcnt(0)
	v_lshl_or_b32 v19, v100, 6, v101
	s_mov_b64 s[0:1], -1
	s_and_b64 vcc, exec, s[34:35]
	v_lshl_add_u32 v20, v18, 2, v213
	s_barrier
	s_cbranch_vccz .LBB0_583
	ds_read_b128 v[22:25], v20
	ds_read_b128 v[26:29], v20 offset:64
	v_mul_u32_u24_e32 v0, 0x88, v19
	v_lshlrev_b32_e32 v0, 1, v0
	v_mov_b32_e32 v21, v187
	s_waitcnt lgkmcnt(1)
	v_pk_mul_f32 v[30:31], v[86:87], v[22:23]
	v_pk_mul_f32 v[32:33], v[74:75], v[22:23]
	v_pk_mul_f32 v[50:51], v[78:79], v[22:23]
	v_pk_mul_f32 v[52:53], v[82:83], v[22:23]
	v_pk_mul_f32 v[70:71], v[88:89], v[24:25]
	v_pk_mul_f32 v[72:73], v[76:77], v[24:25]
	v_pk_mul_f32 v[92:93], v[80:81], v[24:25]
	v_pk_mul_f32 v[94:95], v[84:85], v[24:25]
	s_waitcnt lgkmcnt(0)
	v_pk_mul_f32 v[96:97], v[66:67], v[26:27]
	v_pk_mul_f32 v[98:99], v[54:55], v[26:27]
	v_pk_mul_f32 v[100:101], v[58:59], v[26:27]
	v_pk_mul_f32 v[102:103], v[62:63], v[26:27]
	v_pk_mul_f32 v[104:105], v[68:69], v[28:29]
	ds_read_b128 v[22:25], v20 offset:128
	v_pk_mul_f32 v[106:107], v[56:57], v[28:29]
	v_pk_mul_f32 v[108:109], v[60:61], v[28:29]
	v_pk_mul_f32 v[110:111], v[64:65], v[28:29]
	ds_read_b128 v[26:29], v20 offset:192
	v_cvt_pk_bf16_f32 v32, v32, v33
	v_cvt_pk_bf16_f32 v33, v72, v73
	v_lshl_add_u32 v0, v18, 1, v0
	v_cvt_pk_bf16_f32 v30, v30, v31
	v_cvt_pk_bf16_f32 v31, v70, v71
	v_cvt_pk_bf16_f32 v70, v98, v99
	v_cvt_pk_bf16_f32 v71, v106, v107
	s_waitcnt lgkmcnt(0)
	s_barrier
	v_cvt_pk_bf16_f32 v50, v50, v51
	v_cvt_pk_bf16_f32 v51, v92, v93
	ds_write2_b64 v0, v[32:33], v[70:71] offset1:4
	v_cvt_pk_bf16_f32 v32, v100, v101
	v_cvt_pk_bf16_f32 v33, v108, v109
	v_add_u32_e32 v70, 0x1000, v0
	v_cvt_pk_bf16_f32 v52, v52, v53
	v_cvt_pk_bf16_f32 v53, v94, v95
	ds_write2_b64 v70, v[50:51], v[32:33] offset0:32 offset1:36
	v_cvt_pk_bf16_f32 v32, v102, v103
	v_cvt_pk_bf16_f32 v33, v110, v111
	v_add_u32_e32 v71, 0x2000, v0
	v_pk_mul_f32 v[112:113], v[34:35], v[22:23]
	v_pk_mul_f32 v[114:115], v[38:39], v[22:23]
	v_pk_mul_f32 v[116:117], v[42:43], v[22:23]
	v_pk_mul_f32 v[22:23], v[46:47], v[22:23]
	v_pk_mul_f32 v[118:119], v[36:37], v[24:25]
	v_pk_mul_f32 v[120:121], v[40:41], v[24:25]
	v_pk_mul_f32 v[122:123], v[44:45], v[24:25]
	v_pk_mul_f32 v[24:25], v[48:49], v[24:25]
	v_pk_mul_f32 v[124:125], v[2:3], v[26:27]
	v_pk_mul_f32 v[126:127], v[14:15], v[26:27]
	v_pk_mul_f32 v[128:129], v[10:11], v[26:27]
	v_pk_mul_f32 v[26:27], v[6:7], v[26:27]
	v_pk_mul_f32 v[130:131], v[4:5], v[28:29]
	v_pk_mul_f32 v[132:133], v[16:17], v[28:29]
	v_pk_mul_f32 v[134:135], v[12:13], v[28:29]
	v_pk_mul_f32 v[28:29], v[8:9], v[28:29]
	ds_write2_b64 v71, v[52:53], v[32:33] offset0:64 offset1:68
	v_cvt_pk_bf16_f32 v32, v96, v97
	v_cvt_pk_bf16_f32 v33, v104, v105
	v_add_u32_e32 v52, 0x3000, v0
	ds_write2_b64 v52, v[30:31], v[32:33] offset0:96 offset1:100
	v_cvt_pk_bf16_f32 v30, v114, v115
	v_cvt_pk_bf16_f32 v31, v120, v121
	v_cvt_pk_bf16_f32 v22, v22, v23
	v_cvt_pk_bf16_f32 v23, v24, v25
	v_cvt_pk_bf16_f32 v50, v126, v127
	v_cvt_pk_bf16_f32 v51, v132, v133
	v_cvt_pk_bf16_f32 v26, v26, v27
	v_cvt_pk_bf16_f32 v27, v28, v29
	v_cvt_pk_bf16_f32 v32, v116, v117
	v_cvt_pk_bf16_f32 v33, v122, v123
	v_cvt_pk_bf16_f32 v24, v112, v113
	v_cvt_pk_bf16_f32 v25, v118, v119
	ds_write2_b64 v0, v[30:31], v[50:51] offset0:8 offset1:12
	v_cvt_pk_bf16_f32 v30, v128, v129
	v_cvt_pk_bf16_f32 v31, v134, v135
	ds_write2_b64 v71, v[22:23], v[26:27] offset0:72 offset1:76
	v_cvt_pk_bf16_f32 v22, v124, v125
	v_cvt_pk_bf16_f32 v23, v130, v131
	v_mov_b64_e32 v[26:27], s[40:41]
	ds_write2_b64 v70, v[32:33], v[30:31] offset0:40 offset1:44
	ds_write2_b64 v52, v[24:25], v[22:23] offset0:104 offset1:108
	s_waitcnt lgkmcnt(0)
	s_barrier
; template <class RP>
; __device__ __forceinline__ void epi_staged_bf16_T(f32x4 (&acc)[4][4], int r0, int c0, unsigned char* smem, RP colptr) {
;     ...
; #pragma unroll
;   for (int i = 0; i < 8; ++i) {
;     const int c = t + 256 * i, col = c >> 4, ch = c & 15;
;     *(u32x4*)(colptr(col) + ch * 8) = *(const u32x4*)(Ts + col * PITCH + ch * 8);
;   }
; __device__ __forceinline__ void phase_mix_a(const Params& p, int l, bool last, unsigned char* smem) {
;     ...
;           auto cp = [&](int c) -> u16* { return p.Vt + ((size_t)(b * 4 + h) * 128 + c) * NPOS + pos_base; };
;           epi_staged_bf16_T(acc, r0, c0, smem, cp);
	s_load_dwordx2 s[100:101], s[40:41], 0x158
	s_add_i32 s1, s18, 0xffffc000
	s_and_b32 s19, s18, 0x1f80
	s_ashr_i32 s0, s9, 9
	s_lshr_b32 s1, s1, 8
	s_addk_i32 s19, 0x100
	s_and_b32 s34, s18, 0x80
	v_lshlrev_b32_e32 v0, 4, v21
	s_cmpk_lt_i32 s4, 0x4000
	v_and_b32_e32 v0, 0xf0, v0
	v_ashrrev_i32_e32 v30, 4, v21
	s_cselect_b32 s35, s0, s1
	v_mad_u64_u32 v[22:23], s[0:1], v30, s23, v[0:1]
	s_cselect_b32 s19, s19, s34
	s_lshl_b32 s0, s35, 2
	s_or_b32 s0, s0, s5
	s_ashr_i32 s1, s0, 31
	s_lshl_b64 s[0:1], s[0:1], 7
	v_ashrrev_i32_e32 v31, 31, v30
	ds_read_b128 v[22:25], v22
	v_lshl_add_u64 v[30:31], s[0:1], 0, v[30:31]
	s_lshl_b32 s94, s19, 1
	s_waitcnt lgkmcnt(0)
	v_mov_b32_e32 v28, s100
	v_mov_b32_e32 v29, s101
	v_mad_u64_u32 v[28:29], s[34:35], v30, s68, v[28:29]
	v_mad_i32_i24 v29, v31, s68, v29
	v_lshl_add_u64 v[28:29], v[28:29], 0, s[94:95]
	v_lshl_add_u64 v[28:29], v[28:29], 0, v[0:1]
	global_store_dwordx4 v[28:29], v[22:25], off
	s_load_dwordx2 s[100:101], s[40:41], 0x158
	s_waitcnt lgkmcnt(0)
	v_mov_b32_e32 v28, s100
	v_mov_b32_e32 v29, s101
	s_nop 0
	v_add_u32_e32 v22, 0x100, v21
	v_ashrrev_i32_e32 v22, 4, v22
	v_mad_u64_u32 v[24:25], s[34:35], v22, s23, v[0:1]
	v_ashrrev_i32_e32 v23, 31, v22
	v_lshl_add_u64 v[30:31], s[0:1], 0, v[22:23]
	ds_read_b128 v[22:25], v24
	s_waitcnt lgkmcnt(0)
	v_mad_u64_u32 v[28:29], s[34:35], v30, s68, v[28:29]
	v_mad_i32_i24 v29, v31, s68, v29
	v_lshl_add_u64 v[28:29], v[28:29], 0, s[94:95]
	v_lshl_add_u64 v[28:29], v[28:29], 0, v[0:1]
	global_store_dwordx4 v[28:29], v[22:25], off
	s_load_dwordx2 s[100:101], s[40:41], 0x158
	s_waitcnt lgkmcnt(0)
	v_mov_b32_e32 v28, s100
	v_mov_b32_e32 v29, s101
	s_nop 0
	v_add_u32_e32 v22, 0x200, v21
	v_ashrrev_i32_e32 v22, 4, v22
	v_mad_u64_u32 v[24:25], s[34:35], v22, s23, v[0:1]
	v_ashrrev_i32_e32 v23, 31, v22
	v_lshl_add_u64 v[30:31], s[0:1], 0, v[22:23]
	ds_read_b128 v[22:25], v24
	s_waitcnt lgkmcnt(0)
	v_mad_u64_u32 v[28:29], s[34:35], v30, s68, v[28:29]
	v_mad_i32_i24 v29, v31, s68, v29
	v_lshl_add_u64 v[28:29], v[28:29], 0, s[94:95]
	v_lshl_add_u64 v[28:29], v[28:29], 0, v[0:1]
	global_store_dwordx4 v[28:29], v[22:25], off
	v_mov_b32_e32 v28, s100
	v_mov_b32_e32 v29, s101
	s_nop 0
	v_add_u32_e32 v22, 0x300, v21
	v_ashrrev_i32_e32 v22, 4, v22
	v_mad_u64_u32 v[24:25], s[34:35], v22, s23, v[0:1]
	v_ashrrev_i32_e32 v23, 31, v22
	v_lshl_add_u64 v[30:31], s[0:1], 0, v[22:23]
	ds_read_b128 v[22:25], v24
	s_waitcnt lgkmcnt(0)
	v_mad_u64_u32 v[28:29], s[34:35], v30, s68, v[28:29]
	v_mad_i32_i24 v29, v31, s68, v29
	v_lshl_add_u64 v[28:29], v[28:29], 0, s[94:95]
	v_lshl_add_u64 v[28:29], v[28:29], 0, v[0:1]
	global_store_dwordx4 v[28:29], v[22:25], off
	v_mov_b32_e32 v28, s100
	v_mov_b32_e32 v29, s101
	s_nop 0
	v_add_u32_e32 v22, 0x400, v21
	v_ashrrev_i32_e32 v22, 4, v22
	v_mad_u64_u32 v[24:25], s[34:35], v22, s23, v[0:1]
	v_ashrrev_i32_e32 v23, 31, v22
	v_lshl_add_u64 v[30:31], s[0:1], 0, v[22:23]
	ds_read_b128 v[22:25], v24
	s_waitcnt lgkmcnt(0)
	v_mad_u64_u32 v[28:29], s[34:35], v30, s68, v[28:29]
	v_mad_i32_i24 v29, v31, s68, v29
	v_lshl_add_u64 v[28:29], v[28:29], 0, s[94:95]
	v_lshl_add_u64 v[28:29], v[28:29], 0, v[0:1]
	global_store_dwordx4 v[28:29], v[22:25], off
	v_mov_b32_e32 v28, s100
	v_mov_b32_e32 v29, s101
	s_nop 0
	v_add_u32_e32 v22, 0x500, v21
	v_ashrrev_i32_e32 v22, 4, v22
	v_mad_u64_u32 v[24:25], s[34:35], v22, s23, v[0:1]
	v_ashrrev_i32_e32 v23, 31, v22
	v_lshl_add_u64 v[30:31], s[0:1], 0, v[22:23]
	ds_read_b128 v[22:25], v24
	s_waitcnt lgkmcnt(0)
	v_mad_u64_u32 v[28:29], s[34:35], v30, s68, v[28:29]
	v_mad_i32_i24 v29, v31, s68, v29
	v_lshl_add_u64 v[28:29], v[28:29], 0, s[94:95]
	v_lshl_add_u64 v[28:29], v[28:29], 0, v[0:1]
	global_store_dwordx4 v[28:29], v[22:25], off
	v_mov_b32_e32 v28, s100
	v_mov_b32_e32 v29, s101
	s_nop 0
	v_add_u32_e32 v22, 0x600, v21
	v_ashrrev_i32_e32 v22, 4, v22
	v_mad_u64_u32 v[24:25], s[34:35], v22, s23, v[0:1]
	v_ashrrev_i32_e32 v23, 31, v22
	v_lshl_add_u64 v[30:31], s[0:1], 0, v[22:23]
	ds_read_b128 v[22:25], v24
	v_add_u32_e32 v21, 0x700, v21
	s_waitcnt lgkmcnt(0)
	v_mad_u64_u32 v[28:29], s[34:35], v30, s68, v[28:29]
	v_mad_i32_i24 v29, v31, s68, v29
	v_lshl_add_u64 v[28:29], v[28:29], 0, s[94:95]
	v_lshl_add_u64 v[28:29], v[28:29], 0, v[0:1]
	global_store_dwordx4 v[28:29], v[22:25], off
	v_mov_b32_e32 v26, s100
	v_mov_b32_e32 v27, s101
	s_nop 0
	v_ashrrev_i32_e32 v22, 4, v21
	v_mad_u64_u32 v[24:25], s[34:35], v22, s23, v[0:1]
	v_ashrrev_i32_e32 v23, 31, v22
	v_lshl_add_u64 v[28:29], s[0:1], 0, v[22:23]
	ds_read_b128 v[22:25], v24
	s_waitcnt lgkmcnt(0)
	v_mad_u64_u32 v[26:27], s[0:1], v28, s68, v[26:27]
	v_mad_i32_i24 v27, v29, s68, v27
	v_lshl_add_u64 v[26:27], v[26:27], 0, s[94:95]
	v_lshl_add_u64 v[26:27], v[26:27], 0, v[0:1]
	global_store_dwordx4 v[26:27], v[22:25], off
	s_cbranch_execnz .LBB0_572
	s_branch .LBB0_584

; __device__ __forceinline__ int tid_() { int t = threadIdx.x; asm volatile("" : "+v"(t)); return t; }
; #define XCD_FOR(u, T)                                                                                         \
;   for (int _x = bid_() & 7, _gb = gridDim.x >> 3, _hi = (int)(((long)(_x + 1) * (T)) >> 3),                    \
;            u = (int)(((long)_x * (T)) >> 3) + (bid_() >> 3);                                                  \
;        u < _hi; u += _gb)
; template <int NT, bool BKN, bool MASK = false, bool ROWSS = false, class Epi> ...
;     ...
;   const int t = tid_(), lane = t & 63, wid = t >> 6, wr = wid >> 1, wc = wid & 1, l16 = lane & 15, quad = lane >> 4;
;   const u16* ap[4];
;   const u16* bp[NT];
;   unsigned amask = 0u;
; #pragma unroll
;   for (int i = 0; i < 4; ++i) {
;     const int row = (t >> 3) + 32 * i;
;     const bool v = MASK ? (row < mvalid) : true;
;     amask |= v ? (1u << i) : 0u;
;     int r = v ? row : 0;
;     if (arows) r = arows[r];
;     ap[i] = A + (size_t)r * lda + (t & 7) * 8;
;   }
; #pragma unroll
;   for (int i = 0; i < NT; ++i) {
;     if (!BKN) bp[i] = B + (size_t)((t >> 3) + 32 * i) * ldb + (t & 7) * 8;
;     else { const int c = t + 256 * i; bp[i] = B + (size_t)(c / CPR) * ldb + (c % CPR) * 8; }
;   }
;   const size_t bstep = BKN ? (size_t)64 * ldb : (size_t)64;
;   int nmi = 4;
;   if (MASK) { nmi = (mvalid - wr * 64 + 15) >> 4; nmi = nmi < 0 ? 0 : (nmi > 4 ? 4 : nmi); nmi = __builtin_amdgcn_readfirstlane(nmi); }
;   u32x4 ra0[4], rb0[NT], ra1[4], rb1[NT];
; __device__ __forceinline__ void phase_mix_a(const Params& p, int l, bool last, unsigned char* smem) {
;     ...
;     const int nch = last ? 128 : 132;
;     XCD_FOR(t, nch * 4) {
;       const int ch = t >> 2, h = t & 3, row_base = ch * 128;
.LBB0_600:
	s_mov_b32 s0, s2
	s_and_b32 s4, s0, 7
	s_add_i32 s5, s4, 1
	s_and_b64 s[0:1], exec, s[86:87]
	s_cselect_b32 s0, 0x200, s97
	s_mul_i32 s1, s0, s5
	s_lshr_b32 s8, s1, 3
	s_mov_b32 s1, s2
	s_mul_i32 s0, s0, s4
	s_lshr_b32 s0, s0, 3
	s_ashr_i32 s1, s1, 3
	s_sub_i32 s1, s1, 39
	s_and_b32 s1, s1, 63
	s_add_i32 s9, s1, s0
	s_cmp_ge_i32 s9, s8
	s_cbranch_scc1 .LBB0_605
	s_lshl_b32 s18, s36, 2
	s_lshl_b32 s4, s36, 8
	s_mov_b32 s5, s95
	s_lshl_b32 s19, s9, 5
	s_branch .LBB0_603
.LBB0_602:
	s_or_b64 exec, exec, s[0:1]
	s_and_b32 s1, s9, 3
	s_or_b32 s34, s1, s18
	s_lshl_b32 s94, s34, 7
	v_lshl_add_u64 v[60:61], s[94:95], 2, v[6:7]
	s_waitcnt lgkmcnt(0)
	v_lshl_add_u64 v[2:3], s[4:5], 2, v[8:9]
	s_lshl_b32 s94, s1, 8
	v_mov_b64_e32 v[58:59], s[40:41]
	v_lshl_add_u64 v[62:63], v[2:3], 0, s[94:95]
	global_load_dwordx2 v[2:3], v[58:59], off offset:240
	global_load_dwordx2 v[4:5], v[58:59], off offset:288
	v_mov_b32_e32 v46, v187
	s_ashr_i32 s39, s38, 31
	v_ashrrev_i32_e32 v10, 31, v46
	v_lshrrev_b32_e32 v10, 29, v10
	v_add_u32_e32 v12, v46, v10
	v_ashrrev_i32_e32 v44, 3, v12
	s_lshl_b32 s94, s34, 15
	s_lshl_b64 s[34:35], s[38:39], 11
	v_ashrrev_i32_e32 v45, 31, v44
	v_and_b32_e32 v12, -8, v12
	v_lshlrev_b64 v[10:11], 11, v[44:45]
	v_sub_u32_e32 v45, v46, v12
	v_lshlrev_b32_e32 v42, 3, v45
	v_ashrrev_i32_e32 v43, 31, v42
	v_add_u32_e32 v12, 0x100, v46
	v_lshlrev_b32_e32 v0, 3, v46
	v_and_b32_e32 v20, 56, v0
	v_lshlrev_b32_e32 v0, 1, v20
	s_waitcnt lgkmcnt(0)
	s_barrier
	s_lshl_b32 s0, s1, 6
	v_lshlrev_b32_e32 v67, 2, v20
	v_lshrrev_b32_e32 v47, 4, v46
	v_bfe_u32 v106, v46, 1, 3
	v_bfe_u32 v64, v46, 6, 1
	v_ashrrev_i32_e32 v65, 7, v46
	v_bfe_u32 v66, v46, 4, 2
	s_add_i32 s9, s9, s3
	s_waitcnt vmcnt(0)
	v_lshl_add_u64 v[2:3], v[2:3], 0, s[94:95]
	v_lshl_add_u64 v[4:5], v[4:5], 0, s[34:35]
	s_lshl_b32 s94, s1, 7
	v_lshl_add_u64 v[8:9], v[4:5], 0, s[94:95]
	v_lshl_add_u64 v[10:11], v[8:9], 0, v[10:11]
	v_lshl_add_u64 v[34:35], v[42:43], 1, v[10:11]
	v_ashrrev_i32_e32 v10, 31, v12
	v_lshrrev_b32_e32 v10, 29, v10
	v_add_u32_e32 v13, v12, v10
	v_ashrrev_i32_e32 v40, 3, v13
	v_ashrrev_i32_e32 v41, 31, v40
	v_lshlrev_b64 v[10:11], 11, v[40:41]
	v_ashrrev_i32_e32 v4, 3, v46
	v_lshl_add_u64 v[8:9], v[8:9], 0, v[10:11]
	v_and_b32_e32 v10, -8, v13
	v_ashrrev_i32_e32 v5, 31, v4
	v_sub_u32_e32 v41, v12, v10
	v_lshl_add_u64 v[2:3], v[2:3], 0, v[0:1]
	v_lshlrev_b64 v[4:5], 8, v[4:5]
	v_lshlrev_b32_e32 v38, 3, v41
	v_lshl_add_u64 v[2:3], v[2:3], 0, v[4:5]
	v_ashrrev_i32_e32 v39, 31, v38
	v_lshl_add_u64 v[36:37], v[38:39], 1, v[8:9]
	v_add_co_u32_e32 v8, vcc, s70, v2
	global_load_dwordx4 v[22:25], v[2:3], off
	s_nop 0
	v_addc_co_u32_e32 v9, vcc, 0, v3, vcc
	global_load_dwordx4 v[26:29], v[8:9], off
	v_add_co_u32_e32 v8, vcc, s69, v2
	s_movk_i32 s1, 0x6000
	s_nop 0
	v_addc_co_u32_e32 v9, vcc, 0, v3, vcc
	global_load_dwordx4 v[30:33], v[8:9], off
	s_mov_b64 s[34:35], 0x2000
	v_add_co_u32_e32 v8, vcc, s1, v2
	v_lshl_add_u64 v[4:5], v[2:3], 0, s[34:35]
	v_lshl_add_u64 v[6:7], v[2:3], 0, s[62:63]
	v_addc_co_u32_e32 v9, vcc, 0, v3, vcc
	v_lshl_add_u64 v[18:19], v[2:3], 0, s[24:25]
	global_load_dwordx4 v[48:51], v[8:9], off
	global_load_dwordx4 v[14:17], v[2:3], off offset:128
	global_load_dwordx4 v[10:13], v[4:5], off offset:128
	s_nop 0
	global_load_dwordx4 v[6:9], v[6:7], off offset:128
	s_nop 0
	global_load_dwordx4 v[2:5], v[18:19], off offset:128
	v_or_b32_e32 v18, 0x10200, v67
	ds_read_b128 v[52:55], v18
	v_or_b32_e32 v39, 0x10210, v67
	v_lshlrev_b32_e32 v43, 4, v46
	v_and_b32_e32 v43, 0xffffff80, v43
	v_and_b32_e32 v0, 15, v46
	s_waitcnt vmcnt(0) lgkmcnt(0)
	v_lshlrev_b32_e32 v18, 16, v22
	v_and_b32_e32 v19, 0xffff0000, v22
	v_pk_mul_f32 v[18:19], v[52:53], v[18:19]
	v_lshlrev_b32_e32 v20, 16, v26
	v_and_b32_e32 v21, 0xffff0000, v26
	v_pk_mul_f32 v[20:21], v[52:53], v[20:21]
	v_cvt_pk_bf16_f32 v18, v18, v19
	v_cvt_pk_bf16_f32 v22, v20, v21
	v_lshlrev_b32_e32 v20, 16, v30
	v_and_b32_e32 v21, 0xffff0000, v30
	v_pk_mul_f32 v[20:21], v[52:53], v[20:21]
	s_nop 0
	v_cvt_pk_bf16_f32 v26, v20, v21
	v_lshlrev_b32_e32 v20, 16, v48
	v_and_b32_e32 v21, 0xffff0000, v48
	v_pk_mul_f32 v[20:21], v[52:53], v[20:21]
	v_lshlrev_b32_e32 v48, 16, v28
	v_cvt_pk_bf16_f32 v30, v20, v21
	v_lshlrev_b32_e32 v20, 16, v23
	v_and_b32_e32 v21, 0xffff0000, v23
	v_pk_mul_f32 v[20:21], v[54:55], v[20:21]
	s_nop 0
	v_cvt_pk_bf16_f32 v19, v20, v21
	v_lshlrev_b32_e32 v20, 16, v27
	v_and_b32_e32 v21, 0xffff0000, v27
	v_pk_mul_f32 v[20:21], v[54:55], v[20:21]
	s_nop 0
	v_cvt_pk_bf16_f32 v23, v20, v21
	v_lshlrev_b32_e32 v20, 16, v31
	v_and_b32_e32 v21, 0xffff0000, v31
	v_pk_mul_f32 v[20:21], v[54:55], v[20:21]
	s_nop 0
	v_cvt_pk_bf16_f32 v27, v20, v21
	v_lshlrev_b32_e32 v20, 16, v49
	v_and_b32_e32 v21, 0xffff0000, v49
	v_pk_mul_f32 v[20:21], v[54:55], v[20:21]
	ds_read_b128 v[52:55], v39
	v_and_b32_e32 v49, 0xffff0000, v28
	v_cvt_pk_bf16_f32 v31, v20, v21
	v_lshlrev_b32_e32 v20, 16, v24
	v_and_b32_e32 v21, 0xffff0000, v24
	s_waitcnt lgkmcnt(0)
	v_pk_mul_f32 v[48:49], v[52:53], v[48:49]
	v_pk_mul_f32 v[20:21], v[52:53], v[20:21]
	v_cvt_pk_bf16_f32 v24, v48, v49
	v_lshlrev_b32_e32 v48, 16, v32
	v_and_b32_e32 v49, 0xffff0000, v32
	v_pk_mul_f32 v[48:49], v[52:53], v[48:49]
	v_cvt_pk_bf16_f32 v20, v20, v21
	v_cvt_pk_bf16_f32 v28, v48, v49
	v_lshlrev_b32_e32 v48, 16, v50
	v_and_b32_e32 v49, 0xffff0000, v50
	v_pk_mul_f32 v[48:49], v[52:53], v[48:49]
	v_xor_b32_e32 v39, v47, v46
	v_cvt_pk_bf16_f32 v32, v48, v49
	v_lshlrev_b32_e32 v48, 16, v25
	v_and_b32_e32 v49, 0xffff0000, v25
	v_pk_mul_f32 v[48:49], v[54:55], v[48:49]
	v_lshlrev_b32_e32 v39, 4, v39
	v_cvt_pk_bf16_f32 v21, v48, v49
	v_lshlrev_b32_e32 v48, 16, v29
	v_and_b32_e32 v49, 0xffff0000, v29
	v_pk_mul_f32 v[48:49], v[54:55], v[48:49]
	v_and_or_b32 v68, v39, s14, v43
	v_cvt_pk_bf16_f32 v25, v48, v49
	v_lshlrev_b32_e32 v48, 16, v33
	v_and_b32_e32 v49, 0xffff0000, v33
	v_pk_mul_f32 v[48:49], v[54:55], v[48:49]
	v_lshlrev_b32_e32 v43, 7, v0
	v_cvt_pk_bf16_f32 v29, v48, v49
	v_lshlrev_b32_e32 v48, 16, v51
	v_and_b32_e32 v49, 0xffff0000, v51
	v_pk_mul_f32 v[48:49], v[54:55], v[48:49]
	v_lshl_or_b32 v107, v65, 13, v43
	v_cvt_pk_bf16_f32 v33, v48, v49
	ds_write_b128 v68, v[18:21]
	ds_write_b128 v68, v[22:25] offset:4096
	ds_write_b128 v68, v[26:29] offset:8192
	ds_write_b128 v68, v[30:33] offset:12288
	v_and_b32_e32 v22, -8, v44
	v_lshlrev_b32_e32 v18, 5, v45
	v_lshlrev_b32_e32 v24, 9, v45
	v_bitop3_b32 v25, v18, v22, 32 bitop3:0x6c
	v_and_b32_e32 v23, 7, v44
	v_add_u32_e32 v18, v25, v24
	v_or_b32_e32 v18, v18, v23
	v_lshlrev_b32_e32 v69, 1, v18
	global_load_dwordx4 v[18:21], v[34:35], off offset:512
	v_or_b32_e32 v24, v23, v24
	v_add_lshl_u32 v70, v24, v25, 1
	v_bitop3_b32 v26, v47, v106, 3 bitop3:0x6c
	v_lshl_or_b32 v110, v64, 12, v43
	v_lshlrev_b32_e32 v0, 2, v0
	v_lshl_or_b32 v0, v64, 7, v0
	s_waitcnt vmcnt(0) lgkmcnt(0)
	ds_write_b16 v69, v18 offset:16384
	ds_write_b16_d16_hi v70, v18 offset:16512
	v_or_b32_e32 v18, 2, v42
	v_lshlrev_b32_e32 v24, 6, v18
	v_lshlrev_b32_e32 v18, 2, v18
	v_and_b32_e32 v18, 40, v18
	v_xad_u32 v18, v18, v22, v24
	v_or_b32_e32 v18, v18, v23
	v_lshlrev_b32_e32 v71, 1, v18
	v_or_b32_e32 v18, 3, v42
	v_lshlrev_b32_e32 v24, 6, v18
	v_lshlrev_b32_e32 v18, 2, v18
	v_and_b32_e32 v18, 40, v18
	v_xad_u32 v18, v18, v22, v24
	v_or_b32_e32 v18, v18, v23
	v_lshlrev_b32_e32 v72, 1, v18
	v_or_b32_e32 v18, 4, v42
	ds_write_b16 v71, v19 offset:16384
	ds_write_b16_d16_hi v72, v19 offset:16384
	v_lshlrev_b32_e32 v19, 6, v18
	v_lshlrev_b32_e32 v18, 2, v18
	v_and_b32_e32 v18, 48, v18
	v_xad_u32 v18, v18, v22, v19
	v_or_b32_e32 v18, v18, v23
	v_lshlrev_b32_e32 v73, 1, v18
	v_or_b32_e32 v18, 5, v42
	v_lshlrev_b32_e32 v19, 6, v18
	v_lshlrev_b32_e32 v18, 2, v18
	v_and_b32_e32 v18, 48, v18
	v_xad_u32 v18, v18, v22, v19
	v_or_b32_e32 v18, v18, v23
	v_lshlrev_b32_e32 v74, 1, v18
	v_or_b32_e32 v18, 6, v42
	v_lshlrev_b32_e32 v19, 6, v18
	v_lshlrev_b32_e32 v18, 2, v18
	v_and_b32_e32 v18, 56, v18
	v_xad_u32 v18, v18, v22, v19
	v_or_b32_e32 v18, v18, v23
	v_lshlrev_b32_e32 v75, 1, v18
	v_or_b32_e32 v18, 7, v42
	v_lshlrev_b32_e32 v19, 6, v18
	v_lshlrev_b32_e32 v18, 2, v18
	v_and_b32_e32 v18, 56, v18
	v_xad_u32 v18, v18, v22, v19
	v_or_b32_e32 v18, v18, v23
	v_lshlrev_b32_e32 v76, 1, v18
	v_and_b32_e32 v22, -8, v40
	v_lshlrev_b32_e32 v18, 5, v41
	v_lshlrev_b32_e32 v24, 9, v41
	v_bitop3_b32 v25, v18, v22, 32 bitop3:0x6c
	v_and_b32_e32 v23, 7, v40
	v_add_u32_e32 v18, v25, v24
	v_or_b32_e32 v18, v18, v23
	ds_write_b16 v73, v20 offset:16384
	ds_write_b16_d16_hi v74, v20 offset:16384
	ds_write_b16 v75, v21 offset:16384
	ds_write_b16_d16_hi v76, v21 offset:16384
	v_lshlrev_b32_e32 v77, 1, v18
	global_load_dwordx4 v[18:21], v[36:37], off offset:512
	v_or_b32_e32 v24, v23, v24
	v_add_lshl_u32 v78, v24, v25, 1
	v_lshlrev_b32_e32 v42, 4, v26
	v_or_b32_e32 v121, v42, v107
	v_or_b32_e32 v122, v42, v110
	s_waitcnt vmcnt(0) lgkmcnt(0)
	ds_write_b16 v77, v18 offset:16384
	ds_write_b16_d16_hi v78, v18 offset:16512
	v_or_b32_e32 v18, 2, v38
	v_lshlrev_b32_e32 v24, 6, v18
	v_lshlrev_b32_e32 v18, 2, v18
	v_and_b32_e32 v18, 40, v18
	v_xad_u32 v18, v18, v22, v24
	v_or_b32_e32 v18, v18, v23
	v_lshlrev_b32_e32 v79, 1, v18
	v_or_b32_e32 v18, 3, v38
	v_lshlrev_b32_e32 v24, 6, v18
	v_lshlrev_b32_e32 v18, 2, v18
	v_and_b32_e32 v18, 40, v18
	v_xad_u32 v18, v18, v22, v24
	v_or_b32_e32 v18, v18, v23
	v_lshlrev_b32_e32 v80, 1, v18
	v_or_b32_e32 v18, 4, v38
	ds_write_b16 v79, v19 offset:16384
	ds_write_b16_d16_hi v80, v19 offset:16384
	v_lshlrev_b32_e32 v19, 6, v18
	v_lshlrev_b32_e32 v18, 2, v18
	v_and_b32_e32 v18, 48, v18
	v_xad_u32 v18, v18, v22, v19
	v_or_b32_e32 v18, v18, v23
	v_lshlrev_b32_e32 v81, 1, v18
	v_or_b32_e32 v18, 5, v38
	v_lshlrev_b32_e32 v19, 6, v18
	v_lshlrev_b32_e32 v18, 2, v18
	v_and_b32_e32 v18, 48, v18
	v_xad_u32 v18, v18, v22, v19
	v_or_b32_e32 v18, v18, v23
	v_lshlrev_b32_e32 v118, 1, v18
	v_or_b32_e32 v18, 6, v38
	v_lshlrev_b32_e32 v19, 6, v18
	v_lshlrev_b32_e32 v18, 2, v18
	v_and_b32_e32 v18, 56, v18
	v_xad_u32 v18, v18, v22, v19
	v_or_b32_e32 v18, v18, v23
	v_lshlrev_b32_e32 v119, 1, v18
	v_or_b32_e32 v18, 7, v38
	v_lshlrev_b32_e32 v19, 6, v18
	v_lshlrev_b32_e32 v18, 2, v18
	v_and_b32_e32 v18, 56, v18
	v_xad_u32 v18, v18, v22, v19
	v_or_b32_e32 v18, v18, v23
	v_lshlrev_b32_e32 v120, 1, v18
	v_add_co_u32_e32 v18, vcc, s16, v34
	ds_write_b16 v81, v20 offset:16384
	s_nop 0
	v_addc_co_u32_e32 v19, vcc, 0, v35, vcc
	ds_write_b16_d16_hi v118, v20 offset:16384
	ds_write_b16 v119, v21 offset:16384
	ds_write_b16_d16_hi v120, v21 offset:16384
	global_load_dwordx4 v[18:21], v[18:19], off offset:512
	v_add_co_u32_e32 v22, vcc, s16, v36
	s_nop 1
	v_addc_co_u32_e32 v23, vcc, 0, v37, vcc
	global_load_dwordx4 v[22:25], v[22:23], off offset:512
	s_waitcnt lgkmcnt(0)
	s_barrier
; template <int NT, bool BKN, bool MASK = false, bool ROWSS = false, class Epi> ...
;     ...
;   float ss_[4] = {0.f, 0.f, 0.f, 0.f};
;   int stk_ = 0;
;   f32x4 acc[4][NT];
; #pragma unroll
;   for (int i = 0; i < 4; ++i)
; #pragma unroll
;     for (int j = 0; j < NT; ++j) acc[i][j] = (f32x4){0.f, 0.f, 0.f, 0.f};
;   const int nk = K >> 6;
;   const int nkm1 = nk - 1;
;   __syncthreads();
;   GEMM_LOAD(ra0, rb0, 0);
;   GEMM_LOAD(ra1, rb1, 1);
;   GEMM_STORE(ra0, rb0, 0);
;   GEMM_LOAD(ra0, rb0, (2 < nkm1 ? 2 : nkm1));
;   __syncthreads();
;   for (int kt = 0; kt < nk - 2; kt += 2) {
;     GEMM_COMPUTE(0);
;     GEMM_STORE(ra1, rb1, 1);
;     GEMM_LOAD(ra1, rb1, kt + 3);
;     __syncthreads();
;     GEMM_COMPUTE(1);
;     GEMM_STORE(ra0, rb0, 0);
;     GEMM_LOAD(ra0, rb0, (kt + 4 < nkm1 ? kt + 4 : nkm1));
;     __syncthreads();
;   }
;   GEMM_COMPUTE(0);
;   GEMM_STORE(ra1, rb1, 1);
	ds_read_b128 v[26:29], v121
	ds_read_b128 v[30:33], v121 offset:2048
	ds_read_b128 v[34:37], v121 offset:4096
	ds_read_b128 v[38:41], v121 offset:6144
	ds_read_b128 v[42:45], v122 offset:16384
	ds_read_b128 v[46:49], v122 offset:18432
	s_waitcnt lgkmcnt(0)
	v_mfma_f32_16x16x32_bf16 v[50:53], v[26:29], v[42:45], 0
	v_mfma_f32_16x16x32_bf16 v[54:57], v[26:29], v[46:49], 0
	v_bitop3_b32 v26, v66, v106, 4 bitop3:0x36
	v_lshlrev_b32_e32 v26, 4, v26
	v_or_b32_e32 v123, v26, v107
	v_or_b32_e32 v124, v26, v110
	v_mfma_f32_16x16x32_bf16 v[82:85], v[30:33], v[42:45], 0
	v_mfma_f32_16x16x32_bf16 v[86:89], v[30:33], v[46:49], 0
	v_mfma_f32_16x16x32_bf16 v[94:97], v[34:37], v[46:49], 0
	v_mfma_f32_16x16x32_bf16 v[98:101], v[38:41], v[42:45], 0
	v_mfma_f32_16x16x32_bf16 v[102:105], v[38:41], v[46:49], 0
	ds_read_b128 v[30:33], v123
	ds_read_b128 v[38:41], v123 offset:2048
	ds_read_b128 v[46:49], v123 offset:4096
	ds_read_b128 v[106:109], v123 offset:6144
	ds_read_b128 v[110:113], v124 offset:16384
	ds_read_b128 v[114:117], v124 offset:18432
	v_mfma_f32_16x16x32_bf16 v[90:93], v[34:37], v[42:45], 0
	s_waitcnt lgkmcnt(0)
	v_mfma_f32_16x16x32_bf16 v[34:37], v[38:41], v[110:113], v[82:85]
	s_nop 2
	v_or_b32_e32 v82, 0x10300, v67
	ds_read_b128 v[82:85], v82
	v_mfma_f32_16x16x32_bf16 v[38:41], v[38:41], v[114:117], v[86:89]
	v_or_b32_e32 v67, 0x10310, v67
	s_nop 1
	v_lshlrev_b32_e32 v86, 16, v14
	v_and_b32_e32 v87, 0xffff0000, v14
	s_waitcnt lgkmcnt(0)
	v_pk_mul_f32 v[86:87], v[82:83], v[86:87]
	v_mfma_f32_16x16x32_bf16 v[26:29], v[30:33], v[110:113], v[50:53]
	v_cvt_pk_bf16_f32 v14, v86, v87
	v_lshlrev_b32_e32 v86, 16, v10
	v_and_b32_e32 v87, 0xffff0000, v10
	v_pk_mul_f32 v[86:87], v[82:83], v[86:87]
	v_mfma_f32_16x16x32_bf16 v[30:33], v[30:33], v[114:117], v[54:57]
	v_cvt_pk_bf16_f32 v10, v86, v87
	v_lshlrev_b32_e32 v86, 16, v6
	v_and_b32_e32 v87, 0xffff0000, v6
	v_pk_mul_f32 v[86:87], v[82:83], v[86:87]
	v_mfma_f32_16x16x32_bf16 v[42:45], v[46:49], v[110:113], v[90:93]
	v_cvt_pk_bf16_f32 v6, v86, v87
	v_lshlrev_b32_e32 v86, 16, v2
	v_and_b32_e32 v87, 0xffff0000, v2
	v_pk_mul_f32 v[82:83], v[82:83], v[86:87]
	v_lshlrev_b32_e32 v86, 16, v16
	v_cvt_pk_bf16_f32 v2, v82, v83
	v_lshlrev_b32_e32 v82, 16, v15
	v_and_b32_e32 v83, 0xffff0000, v15
	v_pk_mul_f32 v[82:83], v[84:85], v[82:83]
	v_and_b32_e32 v87, 0xffff0000, v16
	v_cvt_pk_bf16_f32 v15, v82, v83
	v_lshlrev_b32_e32 v82, 16, v11
	v_and_b32_e32 v83, 0xffff0000, v11
	v_pk_mul_f32 v[82:83], v[84:85], v[82:83]
	v_mfma_f32_16x16x32_bf16 v[46:49], v[46:49], v[114:117], v[94:97]
	v_cvt_pk_bf16_f32 v11, v82, v83
	v_lshlrev_b32_e32 v82, 16, v7
	v_and_b32_e32 v83, 0xffff0000, v7
	v_pk_mul_f32 v[82:83], v[84:85], v[82:83]
	v_mfma_f32_16x16x32_bf16 v[50:53], v[106:109], v[110:113], v[98:101]
	v_cvt_pk_bf16_f32 v7, v82, v83
	v_lshlrev_b32_e32 v82, 16, v3
	v_and_b32_e32 v83, 0xffff0000, v3
	v_pk_mul_f32 v[82:83], v[84:85], v[82:83]
	v_mfma_f32_16x16x32_bf16 v[54:57], v[106:109], v[114:117], v[102:105]
	v_cvt_pk_bf16_f32 v3, v82, v83
	ds_read_b128 v[82:85], v67
	s_waitcnt lgkmcnt(0)
	v_pk_mul_f32 v[86:87], v[82:83], v[86:87]
	s_nop 0
	v_cvt_pk_bf16_f32 v16, v86, v87
	v_lshlrev_b32_e32 v86, 16, v12
	v_and_b32_e32 v87, 0xffff0000, v12
	v_pk_mul_f32 v[86:87], v[82:83], v[86:87]
	s_nop 0
	v_cvt_pk_bf16_f32 v12, v86, v87
	v_lshlrev_b32_e32 v86, 16, v8
	v_and_b32_e32 v87, 0xffff0000, v8
	v_pk_mul_f32 v[86:87], v[82:83], v[86:87]
	s_nop 0
	v_cvt_pk_bf16_f32 v8, v86, v87
	v_lshlrev_b32_e32 v86, 16, v4
	v_and_b32_e32 v87, 0xffff0000, v4
	v_pk_mul_f32 v[82:83], v[82:83], v[86:87]
	s_nop 0
	v_cvt_pk_bf16_f32 v4, v82, v83
	v_lshlrev_b32_e32 v82, 16, v17
	v_and_b32_e32 v83, 0xffff0000, v17
	v_pk_mul_f32 v[82:83], v[84:85], v[82:83]
	s_nop 0
	v_cvt_pk_bf16_f32 v17, v82, v83
	v_lshlrev_b32_e32 v82, 16, v13
	v_and_b32_e32 v83, 0xffff0000, v13
	v_pk_mul_f32 v[82:83], v[84:85], v[82:83]
	s_nop 0
	v_cvt_pk_bf16_f32 v13, v82, v83
	v_lshlrev_b32_e32 v82, 16, v9
	v_and_b32_e32 v83, 0xffff0000, v9
	v_pk_mul_f32 v[82:83], v[84:85], v[82:83]
	s_nop 0
	v_cvt_pk_bf16_f32 v9, v82, v83
	v_lshlrev_b32_e32 v82, 16, v5
	v_and_b32_e32 v83, 0xffff0000, v5
	v_pk_mul_f32 v[82:83], v[84:85], v[82:83]
	s_nop 0
	v_cvt_pk_bf16_f32 v5, v82, v83
	ds_write_b128 v68, v[14:17] offset:32768
	ds_write_b128 v68, v[10:13] offset:36864
	ds_write_b128 v68, v[6:9] offset:40960
	ds_write_b128 v68, v[2:5] offset:45056
	s_waitcnt vmcnt(0)
	ds_write_b16 v69, v18 offset:49152
	ds_write_b16_d16_hi v70, v18 offset:49280
	ds_write_b16 v71, v19 offset:49152
	ds_write_b16_d16_hi v72, v19 offset:49152
	ds_write_b16 v73, v20 offset:49152
	ds_write_b16_d16_hi v74, v20 offset:49152
	ds_write_b16 v75, v21 offset:49152
	ds_write_b16_d16_hi v76, v21 offset:49152
	ds_write_b16 v77, v22 offset:49152
	ds_write_b16_d16_hi v78, v22 offset:49280
	ds_write_b16 v79, v23 offset:49152
	ds_write_b16_d16_hi v80, v23 offset:49152
	ds_write_b16 v81, v24 offset:49152
	ds_write_b16_d16_hi v118, v24 offset:49152
	ds_write_b16 v119, v25 offset:49152
	ds_write_b16_d16_hi v120, v25 offset:49152
	s_waitcnt lgkmcnt(0)
	s_barrier
; __device__ __forceinline__ int tid_() { int t = threadIdx.x; asm volatile("" : "+v"(t)); return t; }
; __device__ __forceinline__ void phase_mix_a(const Params& p, int l, bool last, unsigned char* smem) {
;     ...
;       auto epi = [&](f32x4(&acc)[4][2], int r0, int c0) {
;         float* Ts = (float*)smem;
;         const int t2 = tid_();
;         __syncthreads();
; #pragma unroll
;         for (int mi = 0; mi < 4; ++mi)
; #pragma unroll
;           for (int ni = 0; ni < 2; ++ni)
; #pragma unroll
;             for (int j = 0; j < 4; ++j) {
;               const int pr = r0 + mi * 16 + j;
;               Ts[pr * 68 + c0 + ni * 16] = acc[mi][ni][j] * sgn[c0 + ni * 16] + bs[pr];
;             }
;         __syncthreads();
	ds_read_b128 v[2:5], v121 offset:32768
	ds_read_b128 v[6:9], v121 offset:34816
	ds_read_b128 v[10:13], v121 offset:36864
	ds_read_b128 v[14:17], v121 offset:38912
	ds_read_b128 v[18:21], v122 offset:49152
	ds_read_b128 v[22:25], v122 offset:51200
	s_waitcnt lgkmcnt(1)
	v_mfma_f32_16x16x32_bf16 v[26:29], v[2:5], v[18:21], v[26:29]
	s_waitcnt lgkmcnt(0)
	v_mfma_f32_16x16x32_bf16 v[2:5], v[2:5], v[22:25], v[30:33]
	v_mfma_f32_16x16x32_bf16 v[30:33], v[6:9], v[18:21], v[34:37]
	v_mfma_f32_16x16x32_bf16 v[6:9], v[6:9], v[22:25], v[38:41]
	v_mfma_f32_16x16x32_bf16 v[34:37], v[10:13], v[18:21], v[42:45]
	v_mfma_f32_16x16x32_bf16 v[10:13], v[10:13], v[22:25], v[46:49]
	v_mfma_f32_16x16x32_bf16 v[18:21], v[14:17], v[18:21], v[50:53]
	v_mfma_f32_16x16x32_bf16 v[14:17], v[14:17], v[22:25], v[54:57]
	ds_read_b128 v[22:25], v123 offset:32768
	ds_read_b128 v[38:41], v123 offset:34816
	ds_read_b128 v[42:45], v123 offset:36864
	ds_read_b128 v[46:49], v123 offset:38912
	ds_read_b128 v[50:53], v124 offset:49152
	ds_read_b128 v[54:57], v124 offset:51200
	s_waitcnt lgkmcnt(1)
	v_mfma_f32_16x16x32_bf16 v[26:29], v[22:25], v[50:53], v[26:29]
	s_waitcnt lgkmcnt(0)
	v_mfma_f32_16x16x32_bf16 v[22:25], v[22:25], v[54:57], v[2:5]
	v_mfma_f32_16x16x32_bf16 v[2:5], v[46:49], v[54:57], v[14:17]
	s_nop 2
	v_lshlrev_b32_e32 v14, 6, v65
	v_mfma_f32_16x16x32_bf16 v[30:33], v[38:41], v[50:53], v[30:33]
	v_mfma_f32_16x16x32_bf16 v[38:41], v[38:41], v[54:57], v[6:9]
	v_mfma_f32_16x16x32_bf16 v[6:9], v[46:49], v[50:53], v[18:21]
	s_nop 2
	v_lshl_or_b32 v18, v66, 2, v14
	v_ashrrev_i32_e32 v19, 31, v18
	v_mov_b32_e32 v20, v187
	v_lshl_add_u64 v[14:15], v[62:63], 0, v[0:1]
	v_lshl_add_u64 v[16:17], v[18:19], 2, v[60:61]
	s_barrier
	global_load_dword v100, v[14:15], off
	global_load_dword v101, v[14:15], off offset:64
	global_load_dwordx4 v[104:107], v[16:17], off offset:0
	global_load_dwordx4 v[108:111], v[16:17], off offset:64
	global_load_dwordx4 v[112:115], v[16:17], off offset:128
	global_load_dwordx4 v[116:119], v[16:17], off offset:192
	s_waitcnt vmcnt(0)
	v_mov_b32_e32 v21, v100
	v_mov_b32_e32 v19, v104
	v_mfma_f32_16x16x32_bf16 v[34:37], v[42:45], v[50:53], v[34:37]
	s_waitcnt lgkmcnt(0)
	v_fmac_f32_e32 v19, v26, v21
	v_mfma_f32_16x16x32_bf16 v[10:13], v[42:45], v[54:57], v[10:13]
	v_mad_u64_u32 v[42:43], s[34:35], v18, s23, v[0:1]
	ds_write_b32 v42, v19
	v_mov_b32_e32 v19, v100
	v_mov_b32_e32 v21, v105
	v_or_b32_e32 v18, 1, v18
	s_waitcnt lgkmcnt(0)
	v_fmac_f32_e32 v21, v27, v19
	v_mad_u64_u32 v[18:19], s[34:35], v18, s23, v[0:1]
	ds_write_b32 v18, v21
	v_mov_b32_e32 v0, v100
	v_mov_b32_e32 v19, v106
	s_waitcnt lgkmcnt(0)
	v_fmac_f32_e32 v19, v28, v0
	ds_write_b32 v18, v19 offset:272
	v_mov_b32_e32 v0, v100
	v_mov_b32_e32 v19, v107
	s_waitcnt lgkmcnt(0)
	v_fmac_f32_e32 v19, v29, v0
	ds_write_b32 v18, v19 offset:544
	v_mov_b32_e32 v0, v101
	v_mov_b32_e32 v19, v104
	s_waitcnt lgkmcnt(0)
	v_fmac_f32_e32 v19, v22, v0
	ds_write_b32 v42, v19 offset:64
	v_mov_b32_e32 v0, v101
	v_mov_b32_e32 v19, v105
	s_waitcnt lgkmcnt(0)
	v_fmac_f32_e32 v19, v23, v0
	ds_write_b32 v18, v19 offset:64
	v_mov_b32_e32 v0, v101
	v_mov_b32_e32 v19, v106
	s_waitcnt lgkmcnt(0)
	v_fmac_f32_e32 v19, v24, v0
	ds_write_b32 v18, v19 offset:336
	v_mov_b32_e32 v0, v101
	v_mov_b32_e32 v19, v107
	s_waitcnt lgkmcnt(0)
	v_fmac_f32_e32 v19, v25, v0
	ds_write_b32 v18, v19 offset:608
	v_mov_b32_e32 v0, v100
	v_mov_b32_e32 v19, v108
	s_waitcnt lgkmcnt(0)
	v_fmac_f32_e32 v19, v30, v0
	ds_write_b32 v18, v19 offset:4080
	v_mov_b32_e32 v0, v100
	v_mov_b32_e32 v19, v109
	s_waitcnt lgkmcnt(0)
	v_fmac_f32_e32 v19, v31, v0
	ds_write_b32 v18, v19 offset:4352
	v_mov_b32_e32 v0, v100
	v_mov_b32_e32 v19, v110
	s_waitcnt lgkmcnt(0)
	v_fmac_f32_e32 v19, v32, v0
	ds_write_b32 v18, v19 offset:4624
	v_mov_b32_e32 v0, v100
	v_mov_b32_e32 v19, v111
	s_waitcnt lgkmcnt(0)
	v_fmac_f32_e32 v19, v33, v0
	ds_write_b32 v18, v19 offset:4896
	v_mov_b32_e32 v0, v101
	v_mov_b32_e32 v19, v108
	s_waitcnt lgkmcnt(0)
	v_fmac_f32_e32 v19, v38, v0
	ds_write_b32 v18, v19 offset:4144
	v_mov_b32_e32 v0, v101
	v_mov_b32_e32 v19, v109
	s_waitcnt lgkmcnt(0)
	v_fmac_f32_e32 v19, v39, v0
	ds_write_b32 v18, v19 offset:4416
	v_mov_b32_e32 v0, v101
	v_mov_b32_e32 v19, v110
	s_waitcnt lgkmcnt(0)
	v_fmac_f32_e32 v19, v40, v0
	ds_write_b32 v18, v19 offset:4688
	v_mov_b32_e32 v0, v101
	v_mov_b32_e32 v19, v111
	s_waitcnt lgkmcnt(0)
	v_fmac_f32_e32 v19, v41, v0
	ds_write_b32 v18, v19 offset:4960
	v_mov_b32_e32 v0, v100
	v_mov_b32_e32 v19, v112
	s_waitcnt lgkmcnt(0)
	v_fmac_f32_e32 v19, v34, v0
	ds_write_b32 v18, v19 offset:8432
	v_mov_b32_e32 v0, v100
	v_mov_b32_e32 v19, v113
	s_waitcnt lgkmcnt(0)
	v_fmac_f32_e32 v19, v35, v0
	ds_write_b32 v18, v19 offset:8704
	v_mov_b32_e32 v0, v100
	v_mov_b32_e32 v19, v114
	s_waitcnt lgkmcnt(0)
	v_fmac_f32_e32 v19, v36, v0
	ds_write_b32 v18, v19 offset:8976
	v_mov_b32_e32 v0, v100
	v_mov_b32_e32 v19, v115
	s_waitcnt lgkmcnt(0)
	v_fmac_f32_e32 v19, v37, v0
	ds_write_b32 v18, v19 offset:9248
	v_mov_b32_e32 v0, v101
	v_mov_b32_e32 v19, v112
	s_waitcnt lgkmcnt(0)
	v_fmac_f32_e32 v19, v10, v0
	ds_write_b32 v18, v19 offset:8496
	v_mov_b32_e32 v0, v101
	v_mov_b32_e32 v10, v113
	s_waitcnt lgkmcnt(0)
	v_fmac_f32_e32 v10, v11, v0
	ds_write_b32 v18, v10 offset:8768
	v_mov_b32_e32 v0, v101
	v_mov_b32_e32 v10, v114
	s_waitcnt lgkmcnt(0)
	v_fmac_f32_e32 v10, v12, v0
	ds_write_b32 v18, v10 offset:9040
	v_mov_b32_e32 v0, v101
	v_mov_b32_e32 v10, v115
	s_waitcnt lgkmcnt(0)
	v_fmac_f32_e32 v10, v13, v0
	ds_write_b32 v18, v10 offset:9312
	v_mov_b32_e32 v0, v100
	v_mov_b32_e32 v10, v116
	s_waitcnt lgkmcnt(0)
	v_fmac_f32_e32 v10, v6, v0
	ds_write_b32 v18, v10 offset:12784
	v_mov_b32_e32 v0, v100
	v_mov_b32_e32 v6, v117
	s_waitcnt lgkmcnt(0)
	v_fmac_f32_e32 v6, v7, v0
	ds_write_b32 v18, v6 offset:13056
	v_mov_b32_e32 v0, v100
	v_mov_b32_e32 v6, v118
	s_waitcnt lgkmcnt(0)
	v_fmac_f32_e32 v6, v8, v0
	ds_write_b32 v18, v6 offset:13328
	v_mov_b32_e32 v0, v100
	v_mov_b32_e32 v6, v119
	s_waitcnt lgkmcnt(0)
	v_fmac_f32_e32 v6, v9, v0
	ds_write_b32 v18, v6 offset:13600
	v_mov_b32_e32 v0, v101
	v_mov_b32_e32 v6, v116
	s_waitcnt lgkmcnt(0)
	v_fmac_f32_e32 v6, v2, v0
	ds_write_b32 v18, v6 offset:12848
	v_mov_b32_e32 v0, v101
	v_mov_b32_e32 v2, v117
	s_waitcnt lgkmcnt(0)
	v_fmac_f32_e32 v2, v3, v0
	ds_write_b32 v18, v2 offset:13120
	v_mov_b32_e32 v0, v101
	v_mov_b32_e32 v2, v118
	v_ashrrev_i32_e32 v3, 3, v20
	s_waitcnt lgkmcnt(0)
	v_fmac_f32_e32 v2, v4, v0
	ds_write_b32 v18, v2 offset:13392
	v_mov_b32_e32 v0, v101
	v_mov_b32_e32 v2, v119
	v_add_u32_e32 v4, s38, v3
	s_waitcnt lgkmcnt(0)
	v_fmac_f32_e32 v2, v5, v0
	v_ashrrev_i32_e32 v5, 31, v4
	ds_write_b32 v18, v2 offset:13664
	s_waitcnt lgkmcnt(0)
	s_barrier
; __device__ __forceinline__ float bf2f(u16 b) { return __uint_as_float(((unsigned)b) << 16); }
; __device__ __forceinline__ void phase_mix_a(const Params& p, int l, bool last, unsigned char* smem) {
;     ...
; #pragma unroll
;         for (int i = 0; i < 4; ++i) {
;           const int c = t2 + 256 * i, pr = c >> 3, ch = c & 7;
;           const size_t o = (size_t)(row_base + pr) * 1024 + h * 64 + ch * 8;
;           const u32x4 u = *(const u32x4*)(p.PX + o);
;           const float4 z0 = *(const float4*)(Ts + pr * 68 + ch * 8), z1 = *(const float4*)(Ts + pr * 68 + ch * 8 + 4);
;           u32x4 r;
;           r.x = pack2(bf2f((u16)(u.x & 0xffffu)) * z0.x, bf2f((u16)(u.x >> 16)) * z0.y);
;           r.y = pack2(bf2f((u16)(u.y & 0xffffu)) * z0.z, bf2f((u16)(u.y >> 16)) * z0.w);
;           r.z = pack2(bf2f((u16)(u.z & 0xffffu)) * z1.x, bf2f((u16)(u.z >> 16)) * z1.y);
;           r.w = pack2(bf2f((u16)(u.w & 0xffffu)) * z1.z, bf2f((u16)(u.w >> 16)) * z1.w);
;           *(u32x4*)(p.YM + o) = r;
;         }
	global_load_dwordx4 v[4:7], v[58:59], off offset:288
	v_lshlrev_b32_e32 v0, 3, v20
	v_and_b32_e32 v2, 56, v0
	v_lshlrev_b32_e32 v0, 2, v2
	v_lshrrev_b32_e32 v3, 3, v20
	v_add_u32_e32 v8, s38, v3
	v_lshlrev_b32_e32 v8, 10, v8
	v_or3_b32 v8, v8, s0, v2
	v_lshlrev_b32_e32 v22, 1, v8
	v_mov_b32_e32 v23, 0
	v_mad_u32_u24 v30, v3, s23, v0
	v_add_u32_e32 v3, 32, v3
	v_add_u32_e32 v8, s38, v3
	v_lshlrev_b32_e32 v8, 10, v8
	v_or3_b32 v8, v8, s0, v2
	v_lshlrev_b32_e32 v24, 1, v8
	v_mov_b32_e32 v25, 0
	v_mad_u32_u24 v31, v3, s23, v0
	v_add_u32_e32 v3, 32, v3
	v_add_u32_e32 v8, s38, v3
	v_lshlrev_b32_e32 v8, 10, v8
	v_or3_b32 v8, v8, s0, v2
	v_lshlrev_b32_e32 v26, 1, v8
	v_mov_b32_e32 v27, 0
	v_mad_u32_u24 v32, v3, s23, v0
	v_add_u32_e32 v3, 32, v3
	v_add_u32_e32 v8, s38, v3
	v_lshlrev_b32_e32 v8, 10, v8
	v_or3_b32 v8, v8, s0, v2
	v_lshlrev_b32_e32 v28, 1, v8
	v_mov_b32_e32 v29, 0
	v_mad_u32_u24 v33, v3, s23, v0
	ds_read_b128 v[60:63], v30
	ds_read_b128 v[64:67], v30 offset:16
	ds_read_b128 v[68:71], v31
	ds_read_b128 v[72:75], v31 offset:16
	ds_read_b128 v[76:79], v32
	ds_read_b128 v[80:83], v32 offset:16
	ds_read_b128 v[84:87], v33
	ds_read_b128 v[88:91], v33 offset:16
	s_waitcnt vmcnt(0)
	v_lshl_add_u64 v[10:11], v[4:5], 0, v[22:23]
	global_load_dwordx4 v[34:37], v[10:11], off
	v_lshl_add_u64 v[10:11], v[4:5], 0, v[24:25]
	global_load_dwordx4 v[38:41], v[10:11], off
	v_lshl_add_u64 v[10:11], v[4:5], 0, v[26:27]
	global_load_dwordx4 v[42:45], v[10:11], off
	v_lshl_add_u64 v[10:11], v[4:5], 0, v[28:29]
	global_load_dwordx4 v[46:49], v[10:11], off
	s_waitcnt vmcnt(3) lgkmcnt(6)
	v_and_b32_e32 v9, 0xffff0000, v34
	v_lshlrev_b32_e32 v8, 16, v34
	v_pk_mul_f32 v[8:9], v[60:61], v[8:9]
	s_nop 0
	v_cvt_pk_bf16_f32 v34, v8, v9
	v_and_b32_e32 v9, 0xffff0000, v35
	v_lshlrev_b32_e32 v8, 16, v35
	v_pk_mul_f32 v[8:9], v[62:63], v[8:9]
	s_nop 0
	v_cvt_pk_bf16_f32 v35, v8, v9
	v_and_b32_e32 v9, 0xffff0000, v36
	v_lshlrev_b32_e32 v8, 16, v36
	v_pk_mul_f32 v[8:9], v[64:65], v[8:9]
	s_nop 0
	v_cvt_pk_bf16_f32 v36, v8, v9
	v_and_b32_e32 v9, 0xffff0000, v37
	v_lshlrev_b32_e32 v8, 16, v37
	v_pk_mul_f32 v[8:9], v[66:67], v[8:9]
	s_nop 0
	v_cvt_pk_bf16_f32 v37, v8, v9
	v_lshl_add_u64 v[12:13], v[6:7], 0, v[22:23]
	global_store_dwordx4 v[12:13], v[34:37], off
	s_waitcnt vmcnt(3) lgkmcnt(4)
	v_and_b32_e32 v9, 0xffff0000, v38
	v_lshlrev_b32_e32 v8, 16, v38
	v_pk_mul_f32 v[8:9], v[68:69], v[8:9]
	s_nop 0
	v_cvt_pk_bf16_f32 v38, v8, v9
	v_and_b32_e32 v9, 0xffff0000, v39
	v_lshlrev_b32_e32 v8, 16, v39
	v_pk_mul_f32 v[8:9], v[70:71], v[8:9]
	s_nop 0
	v_cvt_pk_bf16_f32 v39, v8, v9
	v_and_b32_e32 v9, 0xffff0000, v40
	v_lshlrev_b32_e32 v8, 16, v40
	v_pk_mul_f32 v[8:9], v[72:73], v[8:9]
	s_nop 0
	v_cvt_pk_bf16_f32 v40, v8, v9
	v_and_b32_e32 v9, 0xffff0000, v41
	v_lshlrev_b32_e32 v8, 16, v41
	v_pk_mul_f32 v[8:9], v[74:75], v[8:9]
	s_nop 0
	v_cvt_pk_bf16_f32 v41, v8, v9
	v_lshl_add_u64 v[12:13], v[6:7], 0, v[24:25]
	global_store_dwordx4 v[12:13], v[38:41], off
	s_waitcnt vmcnt(3) lgkmcnt(2)
	v_and_b32_e32 v9, 0xffff0000, v42
	v_lshlrev_b32_e32 v8, 16, v42
	v_pk_mul_f32 v[8:9], v[76:77], v[8:9]
	s_nop 0
	v_cvt_pk_bf16_f32 v42, v8, v9
	v_and_b32_e32 v9, 0xffff0000, v43
	v_lshlrev_b32_e32 v8, 16, v43
	v_pk_mul_f32 v[8:9], v[78:79], v[8:9]
	s_nop 0
	v_cvt_pk_bf16_f32 v43, v8, v9
	v_and_b32_e32 v9, 0xffff0000, v44
	v_lshlrev_b32_e32 v8, 16, v44
	v_pk_mul_f32 v[8:9], v[80:81], v[8:9]
	s_nop 0
	v_cvt_pk_bf16_f32 v44, v8, v9
	v_and_b32_e32 v9, 0xffff0000, v45
	v_lshlrev_b32_e32 v8, 16, v45
	v_pk_mul_f32 v[8:9], v[82:83], v[8:9]
	s_nop 0
	v_cvt_pk_bf16_f32 v45, v8, v9
	v_lshl_add_u64 v[12:13], v[6:7], 0, v[26:27]
	global_store_dwordx4 v[12:13], v[42:45], off
	s_waitcnt vmcnt(3) lgkmcnt(0)
	v_and_b32_e32 v9, 0xffff0000, v46
	v_lshlrev_b32_e32 v8, 16, v46
	v_pk_mul_f32 v[8:9], v[84:85], v[8:9]
	s_nop 0
	v_cvt_pk_bf16_f32 v46, v8, v9
	v_and_b32_e32 v9, 0xffff0000, v47
	v_lshlrev_b32_e32 v8, 16, v47
	v_pk_mul_f32 v[8:9], v[86:87], v[8:9]
	s_nop 0
	v_cvt_pk_bf16_f32 v47, v8, v9
	v_and_b32_e32 v9, 0xffff0000, v48
	v_lshlrev_b32_e32 v8, 16, v48
	v_pk_mul_f32 v[8:9], v[88:89], v[8:9]
	s_nop 0
	v_cvt_pk_bf16_f32 v48, v8, v9
	v_and_b32_e32 v9, 0xffff0000, v49
	v_lshlrev_b32_e32 v8, 16, v49
	v_pk_mul_f32 v[8:9], v[90:91], v[8:9]
	s_nop 0
	v_cvt_pk_bf16_f32 v49, v8, v9
	v_lshl_add_u64 v[12:13], v[6:7], 0, v[28:29]
	global_store_dwordx4 v[12:13], v[46:49], off
	v_readlane_b32 s0, v254, 45
	s_add_i32 s19, s19, s0
	s_cmp_ge_i32 s9, s8
	s_cbranch_scc1 .LBB0_605

; __device__ __forceinline__ int bid_() { int b = blockIdx.x; asm volatile("" : "+s"(b)); return b; }
; __device__ __forceinline__ void phase_mix_a(const Params& p, int l, bool last, unsigned char* smem) {
;     ...
;   if (!last) {
;     for (int t = bid_(); t < 8; t += gridDim.x) {
;       const int nh = t & 1, mt = (t >> 1) & 1, b = t >> 2;
.LBB0_624:
	s_and_b64 vcc, exec, s[44:45]
	s_cbranch_vccz .LBB0_631
	s_sub_i32 s8, s2, 0x148
	s_cmp_gt_u32 s8, 7
	s_cbranch_scc1 .LBB0_631
	v_mov_b32_e32 v229, v227
	s_lshl_b32 s9, s8, 7

; __device__ __forceinline__ int tid_() { int t = threadIdx.x; asm volatile("" : "+v"(t)); return t; }
; #define XCD_FOR(u, T)                                                                                         \
;   for (int _x = bid_() & 7, _gb = gridDim.x >> 3, _hi = (int)(((long)(_x + 1) * (T)) >> 3),                    \
;            u = (int)(((long)_x * (T)) >> 3) + (bid_() >> 3);                                                  \
;        u < _hi; u += _gb)
; template <int NT, bool BKN, bool MASK = false, bool ROWSS = false, class Epi> ...
;     ...
;   const int t = tid_(), lane = t & 63, wid = t >> 6, wr = wid >> 1, wc = wid & 1, l16 = lane & 15, quad = lane >> 4;
;   const u16* ap[4];
;   const u16* bp[NT];
;   unsigned amask = 0u;
; #pragma unroll
;   for (int i = 0; i < 4; ++i) {
;     const int row = (t >> 3) + 32 * i;
;     const bool v = MASK ? (row < mvalid) : true;
;     amask |= v ? (1u << i) : 0u;
;     int r = v ? row : 0;
;     if (arows) r = arows[r];
;     ap[i] = A + (size_t)r * lda + (t & 7) * 8;
;   }
; #pragma unroll
;   for (int i = 0; i < NT; ++i) {
;     if (!BKN) bp[i] = B + (size_t)((t >> 3) + 32 * i) * ldb + (t & 7) * 8;
;     else { const int c = t + 256 * i; bp[i] = B + (size_t)(c / CPR) * ldb + (c % CPR) * 8; }
;   }
;   const size_t bstep = BKN ? (size_t)64 * ldb : (size_t)64;
; __device__ __forceinline__ void phase_mix_b(const Params& p, int l, bool last, unsigned char* smem) {
;   XCD_FOR(t, 512) {
;     const int nq = t & 3, k2 = (t >> 2) & 63, b = t >> 8;
;     auto epi = [&](f32x4(&acc)[4][2], int r0, int c0) {
;       auto vf = [&](int, int, float v) { return v * 0.001381067932004976f; };
;       auto rp = [&](int k1) -> u16* { return p.YM + (size_t)(b * SEQ + 64 * k1 + k2) * 1024 + 256 + nq * 64; };
;       epi_staged_bf16<2>(acc, r0, c0, smem, vf, rp);
;     };
;     gemm_tile<2, true>(p.M2, 256, nullptr, 128, p.PF + (size_t)(b * 64 + k2) * 2 * 128 * 256 + nq * 64, 256, 256, smem, epi);
.LBB0_685:
	v_mov_b64_e32 v[18:19], s[4:5]
	s_load_dwordx2 s[100:101], s[4:5], 0x100
	s_waitcnt lgkmcnt(0)
	v_mov_b32_e32 v10, s100
	v_mov_b32_e32 v11, s101
	s_load_dwordx2 s[100:101], s[4:5], 0x140
	s_waitcnt lgkmcnt(0)
	v_mov_b32_e32 v12, s100
	v_mov_b32_e32 v13, s101
	v_mov_b32_e32 v4, v187
	s_ashr_i32 s38, s9, 8
	s_nop 0
	v_ashrrev_i32_e32 v2, 3, v4
	v_ashrrev_i32_e32 v7, 31, v4
	v_add_u32_e32 v8, 0x100, v4
	v_lshrrev_b32_e32 v5, 4, v4
	v_and_b32_e32 v29, 15, v4
	v_bfe_u32 v30, v4, 4, 2
	v_bfe_u32 v9, v4, 1, 3
	v_ashrrev_i32_e32 v3, 31, v2
	v_lshrrev_b32_e32 v7, 29, v7
	v_ashrrev_i32_e32 v16, 31, v8
	v_bfe_u32 v28, v4, 6, 1
	v_lshlrev_b32_e32 v6, 4, v4
	v_ashrrev_i32_e32 v31, 7, v4
	v_xor_b32_e32 v17, v5, v4
	v_bitop3_b32 v5, v5, v9, 3 bitop3:0x6c
	v_lshlrev_b32_e32 v20, 7, v29
	v_bitop3_b32 v9, v30, v9, 4 bitop3:0x36
	v_lshlrev_b64 v[14:15], 9, v[2:3]
	v_add_u32_e32 v3, v4, v7
	v_lshrrev_b32_e32 v7, 29, v16
	v_and_b32_e32 v0, 0x70, v6
	v_and_b32_e32 v6, 0xffffff80, v6
	v_lshlrev_b32_e32 v16, 4, v17
	v_lshl_or_b32 v17, v31, 13, v20
	v_lshl_or_b32 v20, v28, 12, v20
	v_lshlrev_b32_e32 v9, 4, v9
	v_ashrrev_i32_e32 v2, 3, v3
	v_and_b32_e32 v21, -8, v3
	v_add_u32_e32 v7, v8, v7
	v_lshlrev_b32_e32 v5, 4, v5
	v_and_or_b32 v36, v16, s14, v6
	v_or_b32_e32 v32, v9, v17
	v_or_b32_e32 v33, v9, v20
	v_ashrrev_i32_e32 v3, 31, v2
	v_sub_u32_e32 v9, v4, v21
	v_ashrrev_i32_e32 v4, 3, v7
	v_and_b32_e32 v16, -8, v7
	v_or_b32_e32 v34, v5, v17
	v_or_b32_e32 v35, v5, v20
	v_and_b32_e32 v17, -8, v2
	v_and_b32_e32 v20, 7, v2
	v_lshlrev_b64 v[6:7], 9, v[2:3]
	v_lshlrev_b32_e32 v2, 3, v9
	v_ashrrev_i32_e32 v5, 31, v4
	v_sub_u32_e32 v16, v8, v16
	v_lshlrev_b32_e32 v21, 9, v9
	v_lshlrev_b32_e32 v22, 5, v9
	v_and_b32_e32 v23, -8, v4
	v_and_b32_e32 v24, 7, v4
	v_lshlrev_b64 v[8:9], 9, v[4:5]
	v_lshlrev_b32_e32 v4, 3, v16
	v_bitop3_b32 v22, v22, v17, 32 bitop3:0x6c
	v_or_b32_e32 v25, v20, v21
	v_or_b32_e32 v26, 2, v2
	v_or_b32_e32 v27, 3, v2
	v_or_b32_e32 v38, 4, v2
	v_or_b32_e32 v39, 5, v2
	v_or_b32_e32 v40, 6, v2
	v_or_b32_e32 v41, 7, v2
	v_lshlrev_b32_e32 v42, 9, v16
	v_lshlrev_b32_e32 v16, 5, v16
	v_add_u32_e32 v21, v22, v21
	v_add_lshl_u32 v37, v25, v22, 1
	v_lshlrev_b32_e32 v22, 6, v26
	v_lshlrev_b32_e32 v25, 2, v26
	v_lshlrev_b32_e32 v26, 6, v27
	v_lshlrev_b32_e32 v27, 2, v27
	v_lshlrev_b32_e32 v43, 6, v38
	v_lshlrev_b32_e32 v38, 2, v38
	v_lshlrev_b32_e32 v44, 6, v39
	v_lshlrev_b32_e32 v39, 2, v39
	v_lshlrev_b32_e32 v45, 6, v40
	v_lshlrev_b32_e32 v40, 2, v40
	v_lshlrev_b32_e32 v46, 6, v41
	v_lshlrev_b32_e32 v41, 2, v41
	v_bitop3_b32 v16, v16, v23, 32 bitop3:0x6c
	v_or_b32_e32 v47, v24, v42
	v_or_b32_e32 v48, 2, v4
	v_or_b32_e32 v49, 3, v4
	s_bfe_u32 s19, s9, 0x60002
	s_and_b32 s0, s18, 0xc0
	s_lshl_b32 s1, s38, 6
	v_or_b32_e32 v50, 4, v4
	v_or_b32_e32 v51, 5, v4
	v_or_b32_e32 v52, 6, v4
	v_or_b32_e32 v53, 7, v4
	v_or_b32_e32 v21, v21, v20
	v_and_b32_e32 v25, 40, v25
	v_and_b32_e32 v27, 40, v27
	v_and_b32_e32 v54, 48, v38
	v_and_b32_e32 v55, 48, v39
	v_and_b32_e32 v40, 56, v40
	v_and_b32_e32 v41, 56, v41
	v_add_u32_e32 v42, v16, v42
	v_add_lshl_u32 v38, v47, v16, 1
	v_lshlrev_b32_e32 v16, 6, v48
	v_lshlrev_b32_e32 v47, 2, v48
	v_lshlrev_b32_e32 v48, 6, v49
	v_lshlrev_b32_e32 v49, 2, v49
	s_lshl_b32 s94, s0, 1
	s_or_b32 s0, s1, s19
	v_lshlrev_b32_e32 v56, 6, v50
	v_lshlrev_b32_e32 v50, 2, v50
	v_lshlrev_b32_e32 v57, 6, v51
	v_lshlrev_b32_e32 v51, 2, v51
	v_lshlrev_b32_e32 v58, 6, v52
	v_lshlrev_b32_e32 v52, 2, v52
	v_lshlrev_b32_e32 v59, 6, v53
	v_lshlrev_b32_e32 v53, 2, v53
	v_lshlrev_b32_e32 v39, 1, v21
	v_xad_u32 v21, v25, v17, v22
	v_xad_u32 v22, v27, v17, v26
	v_xad_u32 v25, v54, v17, v43
	v_xad_u32 v26, v55, v17, v44
	v_xad_u32 v27, v40, v17, v45
	v_xad_u32 v17, v41, v17, v46
	v_or_b32_e32 v40, v42, v24
	v_and_b32_e32 v41, 40, v47
	v_and_b32_e32 v42, 40, v49
	s_ashr_i32 s1, s0, 31
	v_and_b32_e32 v43, 48, v50
	v_and_b32_e32 v44, 48, v51
	v_and_b32_e32 v45, 56, v52
	v_and_b32_e32 v46, 56, v53
	v_or_b32_e32 v21, v21, v20
	v_or_b32_e32 v22, v22, v20
	v_or_b32_e32 v25, v25, v20
	v_or_b32_e32 v26, v26, v20
	v_or_b32_e32 v27, v27, v20
	v_or_b32_e32 v17, v17, v20
	v_xad_u32 v16, v41, v23, v16
	v_xad_u32 v20, v42, v23, v48
	s_lshl_b64 s[0:1], s[0:1], 17
	v_xad_u32 v47, v43, v23, v56
	v_xad_u32 v48, v44, v23, v57
	v_xad_u32 v49, v45, v23, v58
	v_xad_u32 v23, v46, v23, v59
	v_lshlrev_b32_e32 v46, 1, v17
	v_or_b32_e32 v16, v16, v24
	v_or_b32_e32 v17, v20, v24
	v_lshlrev_b32_e32 v41, 1, v21
	v_or_b32_e32 v20, v47, v24
	v_or_b32_e32 v21, v48, v24
	v_lshlrev_b32_e32 v47, 1, v16
	v_lshlrev_b32_e32 v48, 1, v17
	s_waitcnt lgkmcnt(0)
	v_lshl_add_u64 v[12:13], v[12:13], 0, s[0:1]
	v_lshl_add_u64 v[16:17], v[10:11], 0, v[0:1]
	v_lshlrev_b32_e32 v42, 1, v22
	v_lshlrev_b32_e32 v43, 1, v25
	v_or_b32_e32 v22, v49, v24
	v_or_b32_e32 v23, v23, v24
	v_lshl_add_u64 v[10:11], v[12:13], 0, s[94:95]
	v_lshl_add_u64 v[24:25], v[16:17], 0, v[14:15]
	v_lshl_add_u64 v[6:7], v[10:11], 0, v[6:7]
	v_lshl_add_u64 v[8:9], v[10:11], 0, v[8:9]
	v_add_co_u32_e32 v10, vcc, s69, v24
	s_mov_b64 s[0:1], 0xc000
	s_nop 0
	v_addc_co_u32_e32 v11, vcc, 0, v25, vcc
	v_add_co_u32_e32 v12, vcc, s34, v24
	v_lshlrev_b32_e32 v44, 1, v26
	v_lshlrev_b32_e32 v45, 1, v27
	v_lshl_add_u64 v[26:27], v[24:25], 0, s[0:1]
	v_addc_co_u32_e32 v13, vcc, 0, v25, vcc
	s_mov_b32 s0, 0xc000
	v_add_co_u32_e32 v14, vcc, s0, v24
	v_ashrrev_i32_e32 v3, 31, v2
	v_ashrrev_i32_e32 v5, 31, v4
	v_addc_co_u32_e32 v15, vcc, 0, v25, vcc
	s_barrier
	v_lshlrev_b32_e32 v49, 1, v20
	v_lshlrev_b32_e32 v50, 1, v21
	v_lshlrev_b32_e32 v51, 1, v22
	v_lshlrev_b32_e32 v52, 1, v23
	v_lshl_add_u64 v[20:21], v[24:25], 0, s[62:63]
	v_lshl_add_u64 v[22:23], v[24:25], 0, s[10:11]
	global_load_dwordx4 v[54:57], v[24:25], off
	global_load_dwordx4 v[58:61], v[24:25], off offset:128
	v_lshl_add_u64 v[110:111], v[2:3], 1, v[6:7]
	v_lshl_add_u64 v[112:113], v[4:5], 1, v[8:9]
	global_load_dwordx4 v[62:65], v[10:11], off
	global_load_dwordx4 v[66:69], v[12:13], off
	global_load_dwordx4 v[70:73], v[14:15], off
	global_load_dwordx4 v[74:77], v[20:21], off offset:128
	global_load_dwordx4 v[2:5], v[24:25], off offset:256
	global_load_dwordx4 v[78:81], v[22:23], off offset:128
	global_load_dwordx4 v[6:9], v[20:21], off offset:256
	global_load_dwordx4 v[82:85], v[26:27], off offset:128
	global_load_dwordx4 v[10:13], v[22:23], off offset:256
	global_load_dwordx4 v[14:17], v[26:27], off offset:256
	global_load_dwordx4 v[86:89], v[110:111], off
	global_load_dwordx4 v[90:93], v[112:113], off
	v_add_co_u32_e32 v94, vcc, s34, v110
	v_lshlrev_b32_e32 v40, 1, v40
	s_nop 0
	v_addc_co_u32_e32 v95, vcc, 0, v111, vcc
	v_add_co_u32_e32 v98, vcc, s34, v112
	v_lshlrev_b32_e32 v0, 6, v31
	s_nop 0
	v_addc_co_u32_e32 v99, vcc, 0, v113, vcc
	v_add_co_u32_e32 v102, vcc, s15, v110
	v_lshlrev_b32_e32 v29, 1, v29
	s_nop 0
	v_addc_co_u32_e32 v103, vcc, 0, v111, vcc
	v_add_co_u32_e32 v106, vcc, s15, v112
	s_add_i32 s9, s9, s3
	s_nop 0
	v_addc_co_u32_e32 v107, vcc, 0, v113, vcc
	global_load_dwordx4 v[94:97], v[94:95], off
	s_nop 0
	global_load_dwordx4 v[98:101], v[98:99], off
	s_nop 0
	global_load_dwordx4 v[102:105], v[102:103], off
	s_nop 0
	global_load_dwordx4 v[106:109], v[106:107], off
	s_waitcnt vmcnt(0) lgkmcnt(0)
	ds_write_b128 v36, v[54:57]
	ds_write_b128 v36, v[62:65] offset:4096
	ds_write_b128 v36, v[66:69] offset:8192
	ds_write_b128 v36, v[70:73] offset:12288
	ds_write_b16 v39, v86 offset:16384
	ds_write_b16_d16_hi v37, v86 offset:16512
	ds_write_b16 v41, v87 offset:16384
	ds_write_b16_d16_hi v42, v87 offset:16384
	ds_write_b16 v43, v88 offset:16384
	ds_write_b16_d16_hi v44, v88 offset:16384
	ds_write_b16 v45, v89 offset:16384
	ds_write_b16_d16_hi v46, v89 offset:16384
	ds_write_b16 v40, v90 offset:16384
	ds_write_b16_d16_hi v38, v90 offset:16512
	ds_write_b16 v47, v91 offset:16384
	ds_write_b16_d16_hi v48, v91 offset:16384
	ds_write_b16 v49, v92 offset:16384
	ds_write_b16_d16_hi v50, v92 offset:16384
	ds_write_b16 v51, v93 offset:16384
	ds_write_b16_d16_hi v52, v93 offset:16384
	s_waitcnt lgkmcnt(0)
	s_barrier
	ds_read_b128 v[54:57], v34
	ds_read_b128 v[62:65], v35 offset:16384
	ds_read_b128 v[66:69], v34 offset:2048
	ds_read_b128 v[70:73], v35 offset:18432
	ds_read_b128 v[90:93], v34 offset:4096
	v_add_co_u32_e32 v146, vcc, s55, v110
	ds_read_b128 v[114:117], v34 offset:6144
	ds_read_b128 v[118:121], v32
	ds_read_b128 v[122:125], v32 offset:2048
	v_addc_co_u32_e32 v147, vcc, 0, v111, vcc
	v_add_co_u32_e32 v148, vcc, s55, v112
	ds_read_b128 v[126:129], v32 offset:4096
	ds_read_b128 v[130:133], v32 offset:6144
	ds_read_b128 v[134:137], v33 offset:16384
	ds_read_b128 v[142:145], v33 offset:18432
	ds_write_b128 v36, v[58:61] offset:32768
	ds_write_b128 v36, v[74:77] offset:36864
	ds_write_b128 v36, v[78:81] offset:40960
	ds_write_b128 v36, v[82:85] offset:45056
	v_addc_co_u32_e32 v149, vcc, 0, v113, vcc
	s_waitcnt lgkmcnt(11)
	v_mfma_f32_16x16x32_bf16 v[138:141], v[90:93], v[62:65], 0
	global_load_dwordx4 v[74:77], v[24:25], off offset:384
	global_load_dwordx4 v[78:81], v[20:21], off offset:384
	s_nop 0
	global_load_dwordx4 v[20:23], v[22:23], off offset:384
	s_nop 0
	global_load_dwordx4 v[24:27], v[26:27], off offset:384
	s_add_i32 s18, s18, s54
	v_mfma_f32_16x16x32_bf16 v[58:61], v[90:93], v[70:73], 0
	global_load_dwordx4 v[82:85], v[146:147], off
	global_load_dwordx4 v[90:93], v[148:149], off
	ds_write_b16 v39, v94 offset:49152
	ds_write_b16_d16_hi v37, v94 offset:49280
	ds_write_b16 v41, v95 offset:49152
	ds_write_b16_d16_hi v42, v95 offset:49152
	v_mfma_f32_16x16x32_bf16 v[86:89], v[54:57], v[62:65], 0
	ds_write_b16 v43, v96 offset:49152
	ds_write_b16_d16_hi v44, v96 offset:49152
	ds_write_b16 v45, v97 offset:49152
	ds_write_b16_d16_hi v46, v97 offset:49152
	ds_write_b16 v40, v98 offset:49152
	ds_write_b16_d16_hi v38, v98 offset:49280
	ds_write_b16 v47, v99 offset:49152
	ds_write_b16_d16_hi v48, v99 offset:49152
	ds_write_b16 v49, v100 offset:49152
	v_mfma_f32_16x16x32_bf16 v[54:57], v[54:57], v[70:73], 0
	ds_write_b16_d16_hi v50, v100 offset:49152
	ds_write_b16 v51, v101 offset:49152
	ds_write_b16_d16_hi v52, v101 offset:49152
	s_waitcnt lgkmcnt(0)
	s_barrier
; template <int NT, bool BKN, bool MASK = false, bool ROWSS = false, class Epi> ...
;     ...
;   for (int kt = 0; kt < nk - 2; kt += 2) {
;     GEMM_COMPUTE(0);
;     GEMM_STORE(ra1, rb1, 1);
;     GEMM_LOAD(ra1, rb1, kt + 3);
;     __syncthreads();
;     GEMM_COMPUTE(1);
;     GEMM_STORE(ra0, rb0, 0);
;     GEMM_LOAD(ra0, rb0, (kt + 4 < nkm1 ? kt + 4 : nkm1));
;     __syncthreads();
;   }
	v_mfma_f32_16x16x32_bf16 v[110:113], v[66:69], v[62:65], 0
	ds_read_b128 v[98:101], v34 offset:32768
	v_mfma_f32_16x16x32_bf16 v[66:69], v[66:69], v[70:73], 0
	v_mfma_f32_16x16x32_bf16 v[62:65], v[114:117], v[62:65], 0
	v_mfma_f32_16x16x32_bf16 v[70:73], v[114:117], v[70:73], 0
	v_mfma_f32_16x16x32_bf16 v[86:89], v[118:121], v[134:137], v[86:89]
	v_mfma_f32_16x16x32_bf16 v[54:57], v[118:121], v[142:145], v[54:57]
	v_mfma_f32_16x16x32_bf16 v[110:113], v[122:125], v[134:137], v[110:113]
	v_mfma_f32_16x16x32_bf16 v[66:69], v[122:125], v[142:145], v[66:69]
	ds_read_b128 v[114:117], v35 offset:49152
	ds_read_b128 v[118:121], v34 offset:34816
	ds_read_b128 v[122:125], v35 offset:51200
	s_waitcnt lgkmcnt(0)
	v_mfma_f32_16x16x32_bf16 v[86:89], v[98:101], v[114:117], v[86:89]
	v_mfma_f32_16x16x32_bf16 v[54:57], v[98:101], v[122:125], v[54:57]
	v_mfma_f32_16x16x32_bf16 v[98:101], v[118:121], v[114:117], v[110:113]
	v_mfma_f32_16x16x32_bf16 v[66:69], v[118:121], v[122:125], v[66:69]
	s_nop 1
	ds_read_b128 v[110:113], v34 offset:36864
	ds_read_b128 v[118:121], v34 offset:38912
	v_mfma_f32_16x16x32_bf16 v[94:97], v[126:129], v[134:137], v[138:141]
	v_mfma_f32_16x16x32_bf16 v[58:61], v[126:129], v[142:145], v[58:61]
	v_mfma_f32_16x16x32_bf16 v[62:65], v[130:133], v[134:137], v[62:65]
	v_mfma_f32_16x16x32_bf16 v[70:73], v[130:133], v[142:145], v[70:73]
	ds_read_b128 v[126:129], v32 offset:32768
	ds_read_b128 v[130:133], v32 offset:34816
	s_waitcnt lgkmcnt(0)
	v_mfma_f32_16x16x32_bf16 v[94:97], v[110:113], v[114:117], v[94:97]
	v_mfma_f32_16x16x32_bf16 v[58:61], v[110:113], v[122:125], v[58:61]
	ds_read_b128 v[110:113], v32 offset:36864
	ds_read_b128 v[134:137], v32 offset:38912
	ds_read_b128 v[138:141], v33 offset:49152
	v_mfma_f32_16x16x32_bf16 v[62:65], v[118:121], v[114:117], v[62:65]
	ds_read_b128 v[114:117], v33 offset:51200
	ds_write_b128 v36, v[2:5]
	ds_write_b128 v36, v[6:9] offset:4096
	ds_write_b128 v36, v[10:13] offset:8192
	ds_write_b128 v36, v[14:17] offset:12288
	ds_write_b16 v39, v102 offset:16384
	v_mfma_f32_16x16x32_bf16 v[2:5], v[118:121], v[122:125], v[70:73]
	ds_write_b16_d16_hi v37, v102 offset:16512
	ds_write_b16 v41, v103 offset:16384
	ds_write_b16_d16_hi v42, v103 offset:16384
	ds_write_b16 v43, v104 offset:16384
	ds_write_b16_d16_hi v44, v104 offset:16384
	ds_write_b16 v45, v105 offset:16384
	ds_write_b16_d16_hi v46, v105 offset:16384
	ds_write_b16 v40, v106 offset:16384
	ds_write_b16_d16_hi v38, v106 offset:16512
	ds_write_b16 v47, v107 offset:16384
	ds_write_b16_d16_hi v48, v107 offset:16384
	ds_write_b16 v49, v108 offset:16384
	ds_write_b16_d16_hi v50, v108 offset:16384
	ds_write_b16 v51, v109 offset:16384
	ds_write_b16_d16_hi v52, v109 offset:16384
	s_waitcnt lgkmcnt(0)
	s_barrier
	ds_read_b128 v[70:73], v34
	v_mfma_f32_16x16x32_bf16 v[6:9], v[126:129], v[138:141], v[86:89]
	v_mfma_f32_16x16x32_bf16 v[10:13], v[126:129], v[114:117], v[54:57]
	v_mfma_f32_16x16x32_bf16 v[14:17], v[130:133], v[138:141], v[98:101]
	v_mfma_f32_16x16x32_bf16 v[54:57], v[130:133], v[114:117], v[66:69]
	v_mfma_f32_16x16x32_bf16 v[66:69], v[110:113], v[138:141], v[94:97]
	ds_read_b128 v[86:89], v35 offset:16384
	s_nop 1
	ds_read_b128 v[94:97], v34 offset:2048
	ds_read_b128 v[98:101], v35 offset:18432
	v_mfma_f32_16x16x32_bf16 v[58:61], v[110:113], v[114:117], v[58:61]
	s_waitcnt lgkmcnt(0)
	v_mfma_f32_16x16x32_bf16 v[6:9], v[70:73], v[86:89], v[6:9]
	v_mfma_f32_16x16x32_bf16 v[10:13], v[70:73], v[98:101], v[10:13]
	v_mfma_f32_16x16x32_bf16 v[14:17], v[94:97], v[86:89], v[14:17]
	v_mfma_f32_16x16x32_bf16 v[54:57], v[94:97], v[98:101], v[54:57]
	ds_read_b128 v[70:73], v34 offset:4096
	ds_read_b128 v[94:97], v34 offset:6144
	v_mfma_f32_16x16x32_bf16 v[62:65], v[134:137], v[138:141], v[62:65]
	v_mfma_f32_16x16x32_bf16 v[2:5], v[134:137], v[114:117], v[2:5]
	s_waitcnt lgkmcnt(0)
	v_mfma_f32_16x16x32_bf16 v[66:69], v[70:73], v[86:89], v[66:69]
	v_mfma_f32_16x16x32_bf16 v[58:61], v[70:73], v[98:101], v[58:61]
	ds_read_b128 v[70:73], v32
	v_mfma_f32_16x16x32_bf16 v[62:65], v[94:97], v[86:89], v[62:65]
	v_mfma_f32_16x16x32_bf16 v[2:5], v[94:97], v[98:101], v[2:5]
	ds_read_b128 v[86:89], v33 offset:16384
	ds_read_b128 v[94:97], v32 offset:2048
	ds_read_b128 v[98:101], v33 offset:18432
	s_waitcnt lgkmcnt(0)
	v_mfma_f32_16x16x32_bf16 v[6:9], v[70:73], v[86:89], v[6:9]
	v_mfma_f32_16x16x32_bf16 v[10:13], v[70:73], v[98:101], v[10:13]
	v_mfma_f32_16x16x32_bf16 v[14:17], v[94:97], v[86:89], v[14:17]
	v_mfma_f32_16x16x32_bf16 v[54:57], v[94:97], v[98:101], v[54:57]
	ds_read_b128 v[70:73], v32 offset:4096
	ds_read_b128 v[94:97], v32 offset:6144
	s_waitcnt vmcnt(0)
	ds_write_b128 v36, v[74:77] offset:32768
	ds_write_b128 v36, v[78:81] offset:36864
	ds_write_b128 v36, v[20:23] offset:40960
	ds_write_b128 v36, v[24:27] offset:45056
	ds_write_b16 v39, v82 offset:49152
	ds_write_b16_d16_hi v37, v82 offset:49280
	ds_write_b16 v41, v83 offset:49152
	ds_write_b16_d16_hi v42, v83 offset:49152
	ds_write_b16 v43, v84 offset:49152
	ds_write_b16_d16_hi v44, v84 offset:49152
	ds_write_b16 v45, v85 offset:49152
	ds_write_b16_d16_hi v46, v85 offset:49152
	ds_write_b16 v40, v90 offset:49152
	ds_write_b16_d16_hi v38, v90 offset:49280
	ds_write_b16 v47, v91 offset:49152
	ds_write_b16_d16_hi v48, v91 offset:49152
	ds_write_b16 v49, v92 offset:49152
	ds_write_b16_d16_hi v50, v92 offset:49152
	ds_write_b16 v51, v93 offset:49152
	ds_write_b16_d16_hi v52, v93 offset:49152
	s_waitcnt lgkmcnt(0)
	s_barrier
; template <int NT, bool BKN, bool MASK = false, bool ROWSS = false, class Epi> ...
;     ...
;   GEMM_COMPUTE(0);
;   GEMM_STORE(ra1, rb1, 1);
;   __syncthreads();
;   GEMM_COMPUTE(1);
; __device__ __forceinline__ void phase_mix_b(const Params& p, int l, bool last, unsigned char* smem) {
;     ...
;     auto epi = [&](f32x4(&acc)[4][2], int r0, int c0) {
;       auto vf = [&](int, int, float v) { return v * 0.001381067932004976f; };
	ds_read_b128 v[20:23], v34 offset:32768
	ds_read_b128 v[24:27], v35 offset:49152
	ds_read_b128 v[36:39], v34 offset:34816
	ds_read_b128 v[40:43], v35 offset:51200
	s_waitcnt lgkmcnt(2)
	v_mfma_f32_16x16x32_bf16 v[6:9], v[20:23], v[24:27], v[6:9]
	s_waitcnt lgkmcnt(0)
	v_mfma_f32_16x16x32_bf16 v[10:13], v[20:23], v[40:43], v[10:13]
	v_mfma_f32_16x16x32_bf16 v[14:17], v[36:39], v[24:27], v[14:17]
	v_mfma_f32_16x16x32_bf16 v[20:23], v[36:39], v[40:43], v[54:57]
	ds_read_b128 v[36:39], v34 offset:36864
	ds_read_b128 v[44:47], v34 offset:38912
	s_nop 0
	ds_read_b128 v[52:55], v32 offset:32768
	v_mfma_f32_16x16x32_bf16 v[66:69], v[70:73], v[86:89], v[66:69]
	v_mfma_f32_16x16x32_bf16 v[58:61], v[70:73], v[98:101], v[58:61]
	v_mfma_f32_16x16x32_bf16 v[62:65], v[94:97], v[86:89], v[62:65]
	v_mfma_f32_16x16x32_bf16 v[2:5], v[94:97], v[98:101], v[2:5]
	s_waitcnt lgkmcnt(2)
	v_mfma_f32_16x16x32_bf16 v[48:51], v[36:39], v[24:27], v[66:69]
	v_mfma_f32_16x16x32_bf16 v[34:37], v[36:39], v[40:43], v[58:61]
	s_waitcnt lgkmcnt(1)
	v_mfma_f32_16x16x32_bf16 v[24:27], v[44:47], v[24:27], v[62:65]
	s_nop 0
	v_mov_b32_e32 v60, v187
	v_mfma_f32_16x16x32_bf16 v[2:5], v[44:47], v[40:43], v[2:5]
	ds_read_b128 v[38:41], v33 offset:49152
	ds_read_b128 v[42:45], v32 offset:34816
	ds_read_b128 v[56:59], v33 offset:51200
	s_waitcnt lgkmcnt(2)
	v_mfma_f32_16x16x32_bf16 v[6:9], v[52:55], v[38:41], v[6:9]
	s_waitcnt lgkmcnt(0)
	v_mfma_f32_16x16x32_bf16 v[10:13], v[52:55], v[56:59], v[10:13]
	v_mfma_f32_16x16x32_bf16 v[14:17], v[42:45], v[38:41], v[14:17]
	v_mfma_f32_16x16x32_bf16 v[20:23], v[42:45], v[56:59], v[20:23]
	ds_read_b128 v[42:45], v32 offset:36864
	ds_read_b128 v[52:55], v32 offset:38912
	v_lshl_or_b32 v32, v30, 2, v0
	v_lshl_or_b32 v0, v28, 6, v29
	s_waitcnt lgkmcnt(1)
	v_mfma_f32_16x16x32_bf16 v[46:49], v[42:45], v[38:41], v[48:51]
	v_mad_u64_u32 v[32:33], s[0:1], v32, s96, v[0:1]
	v_mul_f32_e32 v0, 0x3ab504f3, v6
	v_mfma_f32_16x16x32_bf16 v[28:31], v[42:45], v[56:59], v[34:37]
	v_mul_f32_e32 v6, 0x3ab504f3, v7
	v_mul_f32_e32 v7, 0x3ab504f3, v8
	v_mul_f32_e32 v8, 0x3ab504f3, v9
	s_waitcnt lgkmcnt(0)
	v_mfma_f32_16x16x32_bf16 v[24:27], v[52:55], v[38:41], v[24:27]
	v_mul_f32_e32 v9, 0x3ab504f3, v10
	v_mul_f32_e32 v10, 0x3ab504f3, v11
	v_mul_f32_e32 v11, 0x3ab504f3, v12
	v_mfma_f32_16x16x32_bf16 v[2:5], v[52:55], v[56:59], v[2:5]
	v_mul_f32_e32 v12, 0x3ab504f3, v13
	v_mul_f32_e32 v13, 0x3ab504f3, v14
	v_mul_f32_e32 v14, 0x3ab504f3, v15
	v_mul_f32_e32 v15, 0x3ab504f3, v16
	v_mul_f32_e32 v16, 0x3ab504f3, v17
	v_mul_f32_e32 v17, 0x3ab504f3, v20
	v_mul_f32_e32 v20, 0x3ab504f3, v21
	v_mul_f32_e32 v21, 0x3ab504f3, v22
	v_mul_f32_e32 v22, 0x3ab504f3, v23
	v_mul_f32_e32 v23, 0x3ab504f3, v46
	v_mul_f32_e32 v33, 0x3ab504f3, v47
	v_mul_f32_e32 v34, 0x3ab504f3, v48
	v_mul_f32_e32 v35, 0x3ab504f3, v49
	v_mul_f32_e32 v28, 0x3ab504f3, v28
	v_mul_f32_e32 v29, 0x3ab504f3, v29
	v_mul_f32_e32 v30, 0x3ab504f3, v30
	v_mul_f32_e32 v31, 0x3ab504f3, v31
	v_mul_f32_e32 v24, 0x3ab504f3, v24
	v_mul_f32_e32 v25, 0x3ab504f3, v25
	v_mul_f32_e32 v26, 0x3ab504f3, v26
	v_mul_f32_e32 v27, 0x3ab504f3, v27
	v_mul_f32_e32 v2, 0x3ab504f3, v2
	v_mul_f32_e32 v3, 0x3ab504f3, v3
	v_mul_f32_e32 v4, 0x3ab504f3, v4
	v_mul_f32_e32 v5, 0x3ab504f3, v5
	v_cvt_pk_bf16_f32 v0, v0, s0
	v_cvt_pk_bf16_f32 v6, v6, s0
	v_cvt_pk_bf16_f32 v7, v7, s0
	s_barrier
; __device__ __forceinline__ u16 f2bf(float f) { return (u16)(pack2(f, 0.f) & 0xffffu); }
; __device__ __forceinline__ int tid_() { int t = threadIdx.x; asm volatile("" : "+v"(t)); return t; }
; template <int NT, class VF, class RP>
; __device__ __forceinline__ void epi_staged_bf16(f32x4 (&acc)[4][NT], int r0, int c0, unsigned char* smem, VF vf, RP rowptr) {
;   constexpr int BN = NT * 32, PITCH = BN + 8, CPR = BN / 8;
;   u16* Ts = (u16*)smem;
;   const int t = tid_();
;   __syncthreads();
; #pragma unroll
;   for (int mi = 0; mi < 4; ++mi)
; #pragma unroll
;     for (int ni = 0; ni < NT; ++ni)
; #pragma unroll
;       for (int j = 0; j < 4; ++j) {
;         const int r = r0 + mi * 16 + j, c = c0 + ni * 16;
;         Ts[r * PITCH + c] = f2bf(vf(r, c, acc[mi][ni][j]));
;       }
;   __syncthreads();
; #pragma unroll
;   for (int i = 0; i < CPR / 2; ++i) {
;     const int c = t + 256 * i, row = c / CPR, ch = c % CPR;
;     u16* d = rowptr(row);
;     if (d) *(u32x4*)(d + ch * 8) = *(const u32x4*)(Ts + row * PITCH + ch * 8);
;   }
	v_cvt_pk_bf16_f32 v8, v8, s0
	v_cvt_pk_bf16_f32 v9, v9, s0
	v_cvt_pk_bf16_f32 v10, v10, s0
	v_cvt_pk_bf16_f32 v11, v11, s0
	v_cvt_pk_bf16_f32 v12, v12, s0
	v_cvt_pk_bf16_f32 v13, v13, s0
	v_cvt_pk_bf16_f32 v14, v14, s0
	v_cvt_pk_bf16_f32 v15, v15, s0
	v_cvt_pk_bf16_f32 v16, v16, s0
	v_cvt_pk_bf16_f32 v17, v17, s0
	v_cvt_pk_bf16_f32 v20, v20, s0
	v_cvt_pk_bf16_f32 v21, v21, s0
	v_cvt_pk_bf16_f32 v22, v22, s0
	v_cvt_pk_bf16_f32 v23, v23, s0
	v_cvt_pk_bf16_f32 v33, v33, s0
	v_cvt_pk_bf16_f32 v34, v34, s0
	v_cvt_pk_bf16_f32 v35, v35, s0
	v_cvt_pk_bf16_f32 v28, v28, s0
	v_cvt_pk_bf16_f32 v29, v29, s0
	v_cvt_pk_bf16_f32 v30, v30, s0
	v_cvt_pk_bf16_f32 v31, v31, s0
	v_cvt_pk_bf16_f32 v24, v24, s0
	v_cvt_pk_bf16_f32 v25, v25, s0
	v_cvt_pk_bf16_f32 v26, v26, s0
	v_cvt_pk_bf16_f32 v27, v27, s0
	v_cvt_pk_bf16_f32 v2, v2, s0
	v_cvt_pk_bf16_f32 v3, v3, s0
	v_cvt_pk_bf16_f32 v4, v4, s0
	v_cvt_pk_bf16_f32 v5, v5, s0
	ds_write_b16 v32, v0
	ds_write_b16 v32, v6 offset:144
	ds_write_b16 v32, v7 offset:288
	ds_write_b16 v32, v8 offset:432
	ds_write_b16 v32, v9 offset:32
	ds_write_b16 v32, v10 offset:176
	ds_write_b16 v32, v11 offset:320
	ds_write_b16 v32, v12 offset:464
	ds_write_b16 v32, v13 offset:2304
	ds_write_b16 v32, v14 offset:2448
	ds_write_b16 v32, v15 offset:2592
	ds_write_b16 v32, v16 offset:2736
	ds_write_b16 v32, v17 offset:2336
	ds_write_b16 v32, v20 offset:2480
	ds_write_b16 v32, v21 offset:2624
	ds_write_b16 v32, v22 offset:2768
	ds_write_b16 v32, v23 offset:4608
	ds_write_b16 v32, v33 offset:4752
	ds_write_b16 v32, v34 offset:4896
	ds_write_b16 v32, v35 offset:5040
	ds_write_b16 v32, v28 offset:4640
	ds_write_b16 v32, v29 offset:4784
	ds_write_b16 v32, v30 offset:4928
	ds_write_b16 v32, v31 offset:5072
	ds_write_b16 v32, v24 offset:6912
	ds_write_b16 v32, v25 offset:7056
	ds_write_b16 v32, v26 offset:7200
	ds_write_b16 v32, v27 offset:7344
	ds_write_b16 v32, v2 offset:6944
	ds_write_b16 v32, v3 offset:7088
	ds_write_b16 v32, v4 offset:7232
	ds_write_b16 v32, v5 offset:7376
	s_waitcnt lgkmcnt(0)
	s_barrier
	global_load_dwordx2 v[6:7], v[18:19], off offset:296
	v_ashrrev_i32_e32 v0, 31, v60
	v_lshrrev_b32_e32 v0, 29, v0
	v_add_u32_e32 v0, v60, v0
	s_lshl_b32 s0, s38, 13
	v_ashrrev_i32_e32 v2, 3, v0
	v_and_b32_e32 v0, -8, v0
	v_lshl_add_u32 v3, v2, 6, s0
	v_sub_u32_e32 v0, v60, v0
	v_mul_lo_u32 v2, v2, s96
	v_or_b32_e32 v8, s19, v3
	v_lshlrev_b32_e32 v10, 3, v0
	v_lshl_add_u32 v0, v0, 4, v2
	v_ashrrev_i32_e32 v9, 31, v8
	ds_read_b128 v[2:5], v0
	v_lshlrev_b64 v[8:9], 11, v[8:9]
	v_ashrrev_i32_e32 v11, 31, v10
	v_add_u32_e32 v0, 0x100, v60
	s_cmp_ge_i32 s9, s8
	s_waitcnt vmcnt(0) lgkmcnt(0)
	v_mov_b32_e32 v12, v6
	v_mov_b32_e32 v13, v7
	v_lshl_add_u64 v[6:7], v[6:7], 0, v[8:9]
	v_lshl_add_u64 v[6:7], v[6:7], 0, s[94:95]
	v_lshl_add_u64 v[6:7], v[10:11], 1, v[6:7]
	global_store_dwordx4 v[6:7], v[2:5], off offset:512
	v_mov_b32_e32 v6, v12
	v_mov_b32_e32 v7, v13
	s_nop 0
	v_ashrrev_i32_e32 v2, 31, v0
	v_lshrrev_b32_e32 v2, 29, v2
	v_add_u32_e32 v2, v0, v2
	v_ashrrev_i32_e32 v3, 3, v2
	v_and_b32_e32 v2, -8, v2
	v_lshl_add_u32 v4, v3, 6, s0
	v_sub_u32_e32 v0, v0, v2
	v_mul_lo_u32 v2, v3, s96
	v_or_b32_e32 v8, s19, v4
	v_lshlrev_b32_e32 v10, 3, v0
	v_lshl_add_u32 v0, v0, 4, v2
	v_ashrrev_i32_e32 v9, 31, v8
	ds_read_b128 v[2:5], v0
	v_lshlrev_b64 v[8:9], 11, v[8:9]
	v_ashrrev_i32_e32 v11, 31, v10
	v_add_u32_e32 v0, 0x200, v60
	s_waitcnt lgkmcnt(0)
	v_lshl_add_u64 v[6:7], v[6:7], 0, v[8:9]
	v_lshl_add_u64 v[6:7], v[6:7], 0, s[94:95]
	v_lshl_add_u64 v[6:7], v[10:11], 1, v[6:7]
	global_store_dwordx4 v[6:7], v[2:5], off offset:512
	v_mov_b32_e32 v6, v12
	v_mov_b32_e32 v7, v13
	s_nop 0
	v_ashrrev_i32_e32 v2, 31, v0
	v_lshrrev_b32_e32 v2, 29, v2
	v_add_u32_e32 v2, v0, v2
	v_ashrrev_i32_e32 v3, 3, v2
	v_and_b32_e32 v2, -8, v2
	v_lshl_add_u32 v4, v3, 6, s0
	v_sub_u32_e32 v0, v0, v2
	v_mul_lo_u32 v2, v3, s96
	v_or_b32_e32 v8, s19, v4
	v_lshlrev_b32_e32 v10, 3, v0
	v_lshl_add_u32 v0, v0, 4, v2
	v_ashrrev_i32_e32 v9, 31, v8
	ds_read_b128 v[2:5], v0
	v_lshlrev_b64 v[8:9], 11, v[8:9]
	v_ashrrev_i32_e32 v11, 31, v10
	v_add_u32_e32 v0, 0x300, v60
	s_waitcnt lgkmcnt(0)
	v_lshl_add_u64 v[6:7], v[6:7], 0, v[8:9]
	v_lshl_add_u64 v[6:7], v[6:7], 0, s[94:95]
	v_lshl_add_u64 v[6:7], v[10:11], 1, v[6:7]
	global_store_dwordx4 v[6:7], v[2:5], off offset:512
	v_mov_b32_e32 v6, v12
	v_mov_b32_e32 v7, v13
	s_nop 0
	v_ashrrev_i32_e32 v2, 31, v0
	v_lshrrev_b32_e32 v2, 29, v2
	v_add_u32_e32 v2, v0, v2
	v_ashrrev_i32_e32 v3, 3, v2
	v_and_b32_e32 v2, -8, v2
	v_lshl_add_u32 v4, v3, 6, s0
	v_sub_u32_e32 v0, v0, v2
	v_mul_lo_u32 v2, v3, s96
	v_or_b32_e32 v8, s19, v4
	v_lshlrev_b32_e32 v10, 3, v0
	v_lshl_add_u32 v0, v0, 4, v2
	v_ashrrev_i32_e32 v9, 31, v8
	ds_read_b128 v[2:5], v0
	v_lshlrev_b64 v[8:9], 11, v[8:9]
	v_ashrrev_i32_e32 v11, 31, v10
	s_waitcnt lgkmcnt(0)
	v_lshl_add_u64 v[6:7], v[6:7], 0, v[8:9]
	v_lshl_add_u64 v[6:7], v[6:7], 0, s[94:95]
	v_lshl_add_u64 v[6:7], v[10:11], 1, v[6:7]
	global_store_dwordx4 v[6:7], v[2:5], off offset:512
	s_cbranch_scc0 .LBB0_685
